# attention: wave-uniform ballot chains (v_cndmask + v_cmp_ne before the uniform branch) replaced by scalar tests of the mask
# speedup vs baseline: 1.0095x; 1.0095x over previous
.LBB0_833:
	s_lshl_b32 s2, s64, 1
	s_or_b32 s2, s2, 1
	s_mul_i32 s12, s2, 0x2400
	v_add_u32_e32 v0, s12, v232
	v_add_u32_e32 v1, v0, v233
	ds_read_b128 v[4:7], v1
	ds_read_b128 v[8:11], v1 offset:32
	ds_read_b128 v[12:15], v1 offset:4608
	ds_read_b128 v[96:99], v1 offset:4640
	ds_read_b128 v[100:103], v1 offset:64
	ds_read_b128 v[104:107], v1 offset:96
	ds_read_b128 v[108:111], v1 offset:4672
	ds_read_b128 v[148:151], v1 offset:4704
	ds_read_b128 v[152:155], v0 offset:128
	ds_read_b128 v[182:185], v0 offset:4736
	s_mulk_i32 s2, 0x3000
	s_setprio 1
	s_waitcnt lgkmcnt(9)
	v_mfma_f32_32x32x16_bf16 v[64:79], v[4:7], v[112:115], v[48:63]
	s_waitcnt lgkmcnt(7)
	v_mfma_f32_32x32x16_bf16 v[80:95], v[12:15], v[112:115], v[48:63]
	s_setprio 0
	v_mfma_f32_32x32x16_bf16 v[64:79], v[8:11], v[116:119], v[64:79]
	v_add_u32_e32 v0, s2, v235
	s_waitcnt lgkmcnt(6)
	v_mfma_f32_32x32x16_bf16 v[80:95], v[96:99], v[116:119], v[80:95]
	s_waitcnt lgkmcnt(5)
	v_mfma_f32_32x32x16_bf16 v[64:79], v[100:103], v[120:123], v[64:79]
	s_waitcnt lgkmcnt(3)
	v_mfma_f32_32x32x16_bf16 v[80:95], v[108:111], v[120:123], v[80:95]
	v_mfma_f32_32x32x16_bf16 v[64:79], v[104:107], v[124:127], v[64:79]
	s_waitcnt lgkmcnt(2)
	v_mfma_f32_32x32x16_bf16 v[80:95], v[148:151], v[124:127], v[80:95]
	ds_read_b64_tr_b16 v[4:5], v0 offset:36864
	ds_read_b64_tr_b16 v[6:7], v0 offset:38400
	ds_read_b64_tr_b16 v[10:11], v0 offset:38464
	ds_read_b64_tr_b16 v[8:9], v0 offset:36928
	ds_read_b64_tr_b16 v[12:13], v0 offset:39936
	ds_read_b64_tr_b16 v[14:15], v0 offset:41472
	ds_read_b64_tr_b16 v[150:151], v0 offset:41536
	ds_read_b64_tr_b16 v[148:149], v0 offset:40000
	s_waitcnt lgkmcnt(9)
	v_mfma_f32_32x32x16_bf16 v[64:79], v[152:155], v[128:131], v[64:79]
	ds_read_b64_tr_b16 v[152:153], v0 offset:43008
	ds_read_b64_tr_b16 v[154:155], v0 offset:44544
	ds_read_b64_tr_b16 v[158:159], v0 offset:44608
	ds_read_b64_tr_b16 v[156:157], v0 offset:43072
	ds_read_b64_tr_b16 v[160:161], v0 offset:46080
	ds_read_b64_tr_b16 v[162:163], v0 offset:47616
	ds_read_b64_tr_b16 v[166:167], v0 offset:47680
	ds_read_b64_tr_b16 v[164:165], v0 offset:46144
	s_waitcnt lgkmcnt(14)
	v_mfma_f32_32x32x16_bf16 v[80:95], v[182:185], v[128:131], v[80:95]
	s_cmp_lg_u32 s66, 0
	s_cselect_b64 s[12:13], -1, 0
	s_sub_i32 s2, s63, 64
	v_cmp_le_i32_e32 vcc, s2, v172
	s_and_b64 s[16:17], s[12:13], vcc
	s_cmp_eq_u64 s[16:17], exec
	s_cbranch_scc1 .LBB0_837
	v_add_u32_e32 v0, s63, v237
	v_add_u32_e32 v1, 0xffffff81, v0
	v_add_u32_e32 v3, 0xffffffa1, v0
	v_cmp_gt_i32_e64 s[16:17], s3, v1
	v_cmp_gt_i32_e64 s[18:19], v3, v172
	s_or_b64 s[16:17], s[16:17], s[18:19]
	v_cmp_le_i32_e32 vcc, v1, v172
	v_cndmask_b32_e64 v80, v80, v244, s[16:17]
	v_add_u32_e32 v3, 0xffffff82, v0
	v_cmp_lt_i32_e64 s[16:17], v1, v172
	v_add_u32_e32 v1, 0xffffffa2, v0
	v_cmp_gt_i32_e64 s[18:19], s3, v3
	v_cmp_gt_i32_e64 s[20:21], v1, v172
	s_or_b64 s[18:19], s[18:19], s[20:21]
	v_add_u32_e32 v1, 0xffffff83, v0
	v_cndmask_b32_e64 v81, v81, v244, s[18:19]
	v_cmp_le_i32_e64 s[18:19], v1, v172
	v_add_u32_e32 v3, 0xffffffa3, v0
	v_cmp_gt_i32_e64 s[20:21], s3, v1
	v_add_u32_e32 v1, s63, v236
	v_cmp_gt_i32_e64 s[22:23], v3, v172
	v_add_u32_e32 v1, 0xffffff81, v1
	s_or_b64 s[20:21], s[20:21], s[22:23]
	v_or_b32_e32 v3, 3, v1
	v_or_b32_e32 v96, 35, v1
	v_cndmask_b32_e64 v82, v82, v244, s[20:21]
	v_cmp_le_i32_e64 s[20:21], v3, v172
	v_cmp_gt_i32_e64 s[22:23], s3, v3
	v_cmp_gt_i32_e64 s[24:25], v96, v172
	v_add_u32_e32 v3, 0xffffff89, v0
	v_add_u32_e32 v96, 0xffffffa9, v0
	s_or_b64 s[22:23], s[22:23], s[24:25]
	v_cmp_gt_i32_e64 s[24:25], s3, v3
	v_cmp_gt_i32_e64 s[26:27], v96, v172
	v_cndmask_b32_e64 v83, v83, v244, s[22:23]
	v_cmp_le_i32_e64 s[22:23], v3, v172
	s_or_b64 s[24:25], s[24:25], s[26:27]
	v_add_u32_e32 v3, 0xffffff8a, v0
	v_add_u32_e32 v96, 0xffffffaa, v0
	v_cndmask_b32_e64 v84, v84, v244, s[24:25]
	v_cmp_le_i32_e64 s[24:25], v3, v172
	v_cmp_gt_i32_e64 s[26:27], s3, v3
	v_cmp_gt_i32_e64 s[28:29], v96, v172
	v_add_u32_e32 v3, 0xffffff8b, v0
	v_add_u32_e32 v96, 0xffffffab, v0
	s_or_b64 s[26:27], s[26:27], s[28:29]
	v_cmp_gt_i32_e64 s[28:29], s3, v3
	v_cmp_gt_i32_e64 s[30:31], v96, v172
	v_cndmask_b32_e64 v85, v85, v244, s[26:27]
	v_cmp_le_i32_e64 s[26:27], v3, v172
	s_or_b64 s[28:29], s[28:29], s[30:31]
	v_or_b32_e32 v3, 11, v1
	v_or_b32_e32 v96, 43, v1
	v_cndmask_b32_e64 v86, v86, v244, s[28:29]
	v_cmp_le_i32_e64 s[28:29], v3, v172
	v_cmp_gt_i32_e64 s[30:31], s3, v3
	v_cmp_gt_i32_e64 s[34:35], v96, v172
	v_add_u32_e32 v3, 0xffffff91, v0
	v_add_u32_e32 v96, 0xffffffb1, v0
	s_or_b64 s[30:31], s[30:31], s[34:35]
	v_cmp_gt_i32_e64 s[34:35], s3, v3
	v_cmp_gt_i32_e64 s[36:37], v96, v172
	v_cndmask_b32_e64 v87, v87, v244, s[30:31]
	v_cmp_le_i32_e64 s[30:31], v3, v172
	s_or_b64 s[34:35], s[34:35], s[36:37]
	v_add_u32_e32 v3, 0xffffff92, v0
	v_add_u32_e32 v96, 0xffffffb2, v0
	v_cndmask_b32_e64 v88, v88, v244, s[34:35]
	v_cmp_le_i32_e64 s[34:35], v3, v172
	v_cmp_gt_i32_e64 s[36:37], s3, v3
	v_cmp_gt_i32_e64 s[38:39], v96, v172
	v_add_u32_e32 v3, 0xffffff93, v0
	v_add_u32_e32 v96, 0xffffffb3, v0
	s_or_b64 s[36:37], s[36:37], s[38:39]
	v_cmp_gt_i32_e64 s[38:39], s3, v3
	v_cmp_gt_i32_e64 s[40:41], v96, v172
	v_cndmask_b32_e64 v89, v89, v244, s[36:37]
	v_cmp_le_i32_e64 s[36:37], v3, v172
	s_or_b64 s[38:39], s[38:39], s[40:41]
	v_or_b32_e32 v3, 19, v1
	v_or_b32_e32 v96, 51, v1
	v_cndmask_b32_e64 v90, v90, v244, s[38:39]
	v_cmp_le_i32_e64 s[38:39], v3, v172
	v_cmp_gt_i32_e64 s[40:41], s3, v3
	v_cmp_gt_i32_e64 s[42:43], v96, v172
	v_add_u32_e32 v3, 0xffffff99, v0
	v_add_u32_e32 v96, 0xffffffb9, v0
	s_or_b64 s[40:41], s[40:41], s[42:43]
	v_cmp_gt_i32_e64 s[42:43], s3, v3
	v_cmp_gt_i32_e64 s[44:45], v96, v172
	v_cndmask_b32_e64 v91, v91, v244, s[40:41]
	v_cmp_le_i32_e64 s[40:41], v3, v172
	s_or_b64 s[42:43], s[42:43], s[44:45]
	v_add_u32_e32 v3, 0xffffff9a, v0
	v_add_u32_e32 v96, 0xffffffba, v0
	v_cndmask_b32_e64 v92, v92, v244, s[42:43]
	v_cmp_le_i32_e64 s[42:43], v3, v172
	v_cmp_gt_i32_e64 s[44:45], s3, v3
	v_cmp_gt_i32_e64 s[46:47], v96, v172
	v_add_u32_e32 v3, 0xffffff9b, v0
	v_add_u32_e32 v0, 0xffffffbb, v0
	s_or_b64 s[44:45], s[44:45], s[46:47]
	v_cmp_gt_i32_e64 s[46:47], s3, v3
	v_cmp_gt_i32_e64 s[48:49], v0, v172
	v_or_b32_e32 v0, 27, v1
	v_or_b32_e32 v1, 59, v1
	s_or_b64 s[46:47], s[46:47], s[48:49]
	v_cmp_gt_i32_e64 s[48:49], s3, v0
	v_cmp_gt_i32_e64 s[50:51], v1, v172
	v_cndmask_b32_e64 v93, v93, v244, s[44:45]
	v_cmp_le_i32_e64 s[44:45], v3, v172
	v_cndmask_b32_e64 v94, v94, v244, s[46:47]
	v_cmp_le_i32_e64 s[46:47], v0, v172
	s_or_b64 s[50:51], s[48:49], s[50:51]
	s_and_saveexec_b64 s[48:49], s[50:51]
	v_mov_b32_e32 v95, s5
	s_or_b64 exec, exec, s[48:49]
	s_and_b64 vcc, s[12:13], vcc
	v_cndmask_b32_e32 v64, v244, v64, vcc
	s_and_b64 vcc, s[12:13], s[16:17]
	v_cndmask_b32_e32 v65, v244, v65, vcc
	s_and_b64 vcc, s[12:13], s[18:19]
	v_cndmask_b32_e32 v66, v244, v66, vcc
	s_and_b64 vcc, s[12:13], s[20:21]
	v_cndmask_b32_e32 v67, v244, v67, vcc
	s_and_b64 vcc, s[12:13], s[22:23]
	v_cndmask_b32_e32 v68, v244, v68, vcc
	s_and_b64 vcc, s[12:13], s[24:25]
	v_cndmask_b32_e32 v69, v244, v69, vcc
	s_and_b64 vcc, s[12:13], s[26:27]
	v_cndmask_b32_e32 v70, v244, v70, vcc
	s_and_b64 vcc, s[12:13], s[28:29]
	v_cndmask_b32_e32 v71, v244, v71, vcc
	s_and_b64 vcc, s[12:13], s[30:31]
	v_cndmask_b32_e32 v72, v244, v72, vcc
	s_and_b64 vcc, s[12:13], s[34:35]
	v_cndmask_b32_e32 v73, v244, v73, vcc
	s_and_b64 vcc, s[12:13], s[36:37]
	v_cndmask_b32_e32 v74, v244, v74, vcc
	s_and_b64 vcc, s[12:13], s[38:39]
	v_cndmask_b32_e32 v75, v244, v75, vcc
	s_and_b64 vcc, s[12:13], s[40:41]
	v_cndmask_b32_e32 v76, v244, v76, vcc
	s_and_b64 vcc, s[12:13], s[42:43]
	v_cndmask_b32_e32 v77, v244, v77, vcc
	s_and_b64 vcc, s[12:13], s[44:45]
	v_cndmask_b32_e32 v78, v244, v78, vcc
	s_and_b64 vcc, s[12:13], s[46:47]
	v_cndmask_b32_e32 v79, v244, v79, vcc
.LBB0_837:
	s_nop 3
	s_xor_b64 s[12:13], s[54:55], -1
	v_max3_f32 v0, v64, v65, v80
	v_max3_f32 v1, v66, v67, v81
	v_max3_f32 v0, v0, v82, v83
	v_max3_f32 v1, v1, v70, v71
	v_max3_f32 v0, v0, v68, v69
	v_max3_f32 v1, v1, v86, v87
	v_max3_f32 v0, v0, v84, v85
	v_max3_f32 v1, v1, v74, v75
	v_max3_f32 v0, v0, v72, v73
	v_max3_f32 v1, v1, v90, v91
	v_max3_f32 v0, v0, v88, v89
	v_max3_f32 v1, v1, v78, v79
	v_max3_f32 v0, v0, v76, v77
	v_max3_f32 v1, v1, v94, v95
	v_max3_f32 v0, v0, v92, v93
	v_max_f32_e32 v0, v0, v1
	v_mov_b32_e32 v1, v0
	s_nop 1
	v_permlane32_swap_b32_e32 v0, v1
	v_max_f32_e32 v1, v0, v1
	v_cmp_lt_f32_e32 vcc, s14, v1
	s_or_b64 s[16:17], vcc, s[12:13]
	s_cbranch_scc0 .LBB0_843
	s_and_saveexec_b64 s[16:17], s[12:13]
	s_xor_b64 s[12:13], exec, s[16:17]
	v_cmp_lg_f32_e64 s[54:55], s5, v1
	s_nop 1
	v_cndmask_b32_e64 v48, 0, v1, s[54:55]
	s_or_saveexec_b64 s[12:13], s[12:13]
	v_mov_b32_e32 v0, 1.0
	s_xor_b64 exec, exec, s[12:13]
	v_max_f32_e32 v0, v1, v1
	v_max_f32_e32 v48, 0, v0
	v_exp_f32_e64 v0, -v48
	s_or_b64 s[54:55], s[54:55], exec
	s_or_b64 exec, exec, s[12:13]
	v_add_f32_e32 v181, v181, v48
	v_pk_add_f32 v[64:65], v[64:65], v[48:49] op_sel_hi:[1,0] neg_lo:[0,1] neg_hi:[0,1]
	v_pk_add_f32 v[80:81], v[80:81], v[48:49] op_sel_hi:[1,0] neg_lo:[0,1] neg_hi:[0,1]
	v_pk_add_f32 v[66:67], v[66:67], v[48:49] op_sel_hi:[1,0] neg_lo:[0,1] neg_hi:[0,1]
	v_pk_add_f32 v[82:83], v[82:83], v[48:49] op_sel_hi:[1,0] neg_lo:[0,1] neg_hi:[0,1]
	v_pk_add_f32 v[68:69], v[68:69], v[48:49] op_sel_hi:[1,0] neg_lo:[0,1] neg_hi:[0,1]
	v_pk_add_f32 v[84:85], v[84:85], v[48:49] op_sel_hi:[1,0] neg_lo:[0,1] neg_hi:[0,1]
	v_pk_add_f32 v[70:71], v[70:71], v[48:49] op_sel_hi:[1,0] neg_lo:[0,1] neg_hi:[0,1]
	v_pk_add_f32 v[86:87], v[86:87], v[48:49] op_sel_hi:[1,0] neg_lo:[0,1] neg_hi:[0,1]
	v_pk_add_f32 v[72:73], v[72:73], v[48:49] op_sel_hi:[1,0] neg_lo:[0,1] neg_hi:[0,1]
	v_pk_add_f32 v[88:89], v[88:89], v[48:49] op_sel_hi:[1,0] neg_lo:[0,1] neg_hi:[0,1]
	v_pk_add_f32 v[74:75], v[74:75], v[48:49] op_sel_hi:[1,0] neg_lo:[0,1] neg_hi:[0,1]
	v_pk_add_f32 v[90:91], v[90:91], v[48:49] op_sel_hi:[1,0] neg_lo:[0,1] neg_hi:[0,1]
	v_pk_add_f32 v[76:77], v[76:77], v[48:49] op_sel_hi:[1,0] neg_lo:[0,1] neg_hi:[0,1]
	v_pk_add_f32 v[92:93], v[92:93], v[48:49] op_sel_hi:[1,0] neg_lo:[0,1] neg_hi:[0,1]
	v_pk_add_f32 v[78:79], v[78:79], v[48:49] op_sel_hi:[1,0] neg_lo:[0,1] neg_hi:[0,1]
	v_pk_add_f32 v[94:95], v[94:95], v[48:49] op_sel_hi:[1,0] neg_lo:[0,1] neg_hi:[0,1]
	v_xor_b32_e32 v48, 0x80000000, v181
	v_mul_f32_e32 v180, v180, v0
	v_pk_mul_f32 v[46:47], v[46:47], v[0:1] op_sel_hi:[1,0]
	v_pk_mul_f32 v[44:45], v[44:45], v[0:1] op_sel_hi:[1,0]
	v_pk_mul_f32 v[42:43], v[42:43], v[0:1] op_sel_hi:[1,0]
	v_pk_mul_f32 v[40:41], v[40:41], v[0:1] op_sel_hi:[1,0]
	v_pk_mul_f32 v[38:39], v[38:39], v[0:1] op_sel_hi:[1,0]
	v_pk_mul_f32 v[36:37], v[36:37], v[0:1] op_sel_hi:[1,0]
	v_pk_mul_f32 v[34:35], v[34:35], v[0:1] op_sel_hi:[1,0]
	v_pk_mul_f32 v[32:33], v[32:33], v[0:1] op_sel_hi:[1,0]
	v_pk_mul_f32 v[30:31], v[30:31], v[0:1] op_sel_hi:[1,0]
	v_pk_mul_f32 v[28:29], v[28:29], v[0:1] op_sel_hi:[1,0]
	v_pk_mul_f32 v[26:27], v[26:27], v[0:1] op_sel_hi:[1,0]
	v_pk_mul_f32 v[24:25], v[24:25], v[0:1] op_sel_hi:[1,0]
	v_pk_mul_f32 v[22:23], v[22:23], v[0:1] op_sel_hi:[1,0]
	v_pk_mul_f32 v[20:21], v[20:21], v[0:1] op_sel_hi:[1,0]
	v_pk_mul_f32 v[18:19], v[18:19], v[0:1] op_sel_hi:[1,0]
	v_pk_mul_f32 v[16:17], v[16:17], v[0:1] op_sel_hi:[1,0]
	v_mov_b32_e32 v49, v48
	v_mov_b32_e32 v50, v48
	v_mov_b32_e32 v51, v48
	v_mov_b32_e32 v52, v48
	v_mov_b32_e32 v53, v48
	v_mov_b32_e32 v54, v48
	v_mov_b32_e32 v55, v48
	v_mov_b32_e32 v56, v48
	v_mov_b32_e32 v57, v48
	v_mov_b32_e32 v58, v48
	v_mov_b32_e32 v59, v48
	v_mov_b32_e32 v60, v48
	v_mov_b32_e32 v61, v48
	v_mov_b32_e32 v62, v48
	v_mov_b32_e32 v63, v48

.LBB0_850:
	s_nop 9
	s_nop 0
	v_max3_f32 v0, v64, v65, v80
	v_max3_f32 v1, v66, v67, v81
	v_max3_f32 v0, v0, v82, v83
	v_max3_f32 v1, v1, v70, v71
	v_max3_f32 v0, v0, v68, v69
	v_max3_f32 v1, v1, v86, v87
	v_max3_f32 v0, v0, v84, v85
	v_max3_f32 v1, v1, v74, v75
	v_max3_f32 v0, v0, v72, v73
	v_max3_f32 v1, v1, v90, v91
	v_max3_f32 v0, v0, v88, v89
	v_max3_f32 v1, v1, v78, v79
	v_max3_f32 v0, v0, v76, v77
	v_max3_f32 v1, v1, v94, v95
	v_max3_f32 v0, v0, v92, v93
	v_max_f32_e32 v0, v0, v1
	v_mov_b32_e32 v1, v0
	s_nop 1
	v_permlane32_swap_b32_e32 v0, v1
	v_max_f32_e32 v1, v0, v1
	v_cmp_lt_f32_e32 vcc, s14, v1
	s_or_b64 s[16:17], vcc, s[12:13]
	s_cbranch_scc0 .LBB0_856
	s_and_saveexec_b64 s[16:17], s[12:13]
	s_xor_b64 s[12:13], exec, s[16:17]
	v_cmp_lg_f32_e64 s[54:55], s5, v1
	s_nop 1
	v_cndmask_b32_e64 v48, 0, v1, s[54:55]
	s_or_saveexec_b64 s[12:13], s[12:13]
	v_mov_b32_e32 v0, 1.0
	s_xor_b64 exec, exec, s[12:13]
	v_max_f32_e32 v0, v1, v1
	v_max_f32_e32 v48, 0, v0
	v_exp_f32_e64 v0, -v48
	s_or_b64 s[54:55], s[54:55], exec
	s_or_b64 exec, exec, s[12:13]
	v_add_f32_e32 v181, v181, v48
	v_pk_add_f32 v[64:65], v[64:65], v[48:49] op_sel_hi:[1,0] neg_lo:[0,1] neg_hi:[0,1]
	v_pk_add_f32 v[80:81], v[80:81], v[48:49] op_sel_hi:[1,0] neg_lo:[0,1] neg_hi:[0,1]
	v_pk_add_f32 v[66:67], v[66:67], v[48:49] op_sel_hi:[1,0] neg_lo:[0,1] neg_hi:[0,1]
	v_pk_add_f32 v[82:83], v[82:83], v[48:49] op_sel_hi:[1,0] neg_lo:[0,1] neg_hi:[0,1]
	v_pk_add_f32 v[68:69], v[68:69], v[48:49] op_sel_hi:[1,0] neg_lo:[0,1] neg_hi:[0,1]
	v_pk_add_f32 v[84:85], v[84:85], v[48:49] op_sel_hi:[1,0] neg_lo:[0,1] neg_hi:[0,1]
	v_pk_add_f32 v[70:71], v[70:71], v[48:49] op_sel_hi:[1,0] neg_lo:[0,1] neg_hi:[0,1]
	v_pk_add_f32 v[86:87], v[86:87], v[48:49] op_sel_hi:[1,0] neg_lo:[0,1] neg_hi:[0,1]
	v_pk_add_f32 v[72:73], v[72:73], v[48:49] op_sel_hi:[1,0] neg_lo:[0,1] neg_hi:[0,1]
	v_pk_add_f32 v[88:89], v[88:89], v[48:49] op_sel_hi:[1,0] neg_lo:[0,1] neg_hi:[0,1]
	v_pk_add_f32 v[74:75], v[74:75], v[48:49] op_sel_hi:[1,0] neg_lo:[0,1] neg_hi:[0,1]
	v_pk_add_f32 v[90:91], v[90:91], v[48:49] op_sel_hi:[1,0] neg_lo:[0,1] neg_hi:[0,1]
	v_pk_add_f32 v[76:77], v[76:77], v[48:49] op_sel_hi:[1,0] neg_lo:[0,1] neg_hi:[0,1]
	v_pk_add_f32 v[92:93], v[92:93], v[48:49] op_sel_hi:[1,0] neg_lo:[0,1] neg_hi:[0,1]
	v_pk_add_f32 v[78:79], v[78:79], v[48:49] op_sel_hi:[1,0] neg_lo:[0,1] neg_hi:[0,1]
	v_pk_add_f32 v[94:95], v[94:95], v[48:49] op_sel_hi:[1,0] neg_lo:[0,1] neg_hi:[0,1]
	v_xor_b32_e32 v48, 0x80000000, v181
	v_mul_f32_e32 v180, v180, v0
	v_pk_mul_f32 v[46:47], v[46:47], v[0:1] op_sel_hi:[1,0]
	v_pk_mul_f32 v[44:45], v[44:45], v[0:1] op_sel_hi:[1,0]
	v_pk_mul_f32 v[42:43], v[42:43], v[0:1] op_sel_hi:[1,0]
	v_pk_mul_f32 v[40:41], v[40:41], v[0:1] op_sel_hi:[1,0]
	v_pk_mul_f32 v[38:39], v[38:39], v[0:1] op_sel_hi:[1,0]
	v_pk_mul_f32 v[36:37], v[36:37], v[0:1] op_sel_hi:[1,0]
	v_pk_mul_f32 v[34:35], v[34:35], v[0:1] op_sel_hi:[1,0]
	v_pk_mul_f32 v[32:33], v[32:33], v[0:1] op_sel_hi:[1,0]
	v_pk_mul_f32 v[30:31], v[30:31], v[0:1] op_sel_hi:[1,0]
	v_pk_mul_f32 v[28:29], v[28:29], v[0:1] op_sel_hi:[1,0]
	v_pk_mul_f32 v[26:27], v[26:27], v[0:1] op_sel_hi:[1,0]
	v_pk_mul_f32 v[24:25], v[24:25], v[0:1] op_sel_hi:[1,0]
	v_pk_mul_f32 v[22:23], v[22:23], v[0:1] op_sel_hi:[1,0]
	v_pk_mul_f32 v[20:21], v[20:21], v[0:1] op_sel_hi:[1,0]
	v_pk_mul_f32 v[18:19], v[18:19], v[0:1] op_sel_hi:[1,0]
	v_pk_mul_f32 v[16:17], v[16:17], v[0:1] op_sel_hi:[1,0]
	v_mov_b32_e32 v49, v48
	v_mov_b32_e32 v50, v48
	v_mov_b32_e32 v51, v48
	v_mov_b32_e32 v52, v48
	v_mov_b32_e32 v53, v48
	v_mov_b32_e32 v54, v48
	v_mov_b32_e32 v55, v48
	v_mov_b32_e32 v56, v48
	v_mov_b32_e32 v57, v48
	v_mov_b32_e32 v58, v48
	v_mov_b32_e32 v59, v48
	v_mov_b32_e32 v60, v48
	v_mov_b32_e32 v61, v48
	v_mov_b32_e32 v62, v48
	v_mov_b32_e32 v63, v48

.LBB0_878:
	s_nop 8
	s_xor_b64 s[16:17], s[52:53], -1
	v_max3_f32 v0, v80, v81, v96
	v_max3_f32 v1, v82, v83, v97
	v_max3_f32 v0, v0, v98, v99
	v_max3_f32 v1, v1, v86, v87
	v_max3_f32 v0, v0, v84, v85
	v_max3_f32 v1, v1, v102, v103
	v_max3_f32 v0, v0, v100, v101
	v_max3_f32 v1, v1, v90, v91
	v_max3_f32 v0, v0, v88, v89
	v_max3_f32 v1, v1, v106, v107
	v_max3_f32 v0, v0, v104, v105
	v_max3_f32 v1, v1, v94, v95
	v_max3_f32 v0, v0, v92, v93
	v_max3_f32 v1, v1, v110, v111
	v_max3_f32 v0, v0, v108, v109
	v_max_f32_e32 v0, v0, v1
	v_mov_b32_e32 v1, v0
	s_nop 1
	v_permlane32_swap_b32_e32 v0, v1
	v_max_f32_e32 v1, v0, v1
	v_cmp_lt_f32_e32 vcc, s14, v1
	s_or_b64 s[18:19], vcc, s[16:17]
	s_cbranch_scc0 .LBB0_884
	s_and_saveexec_b64 s[18:19], s[16:17]
	s_xor_b64 s[16:17], exec, s[18:19]
	v_cmp_lg_f32_e64 s[52:53], s5, v1
	s_nop 1
	v_cndmask_b32_e64 v48, 0, v1, s[52:53]
	s_or_saveexec_b64 s[16:17], s[16:17]
	v_mov_b32_e32 v0, 1.0
	s_xor_b64 exec, exec, s[16:17]
	v_max_f32_e32 v0, v1, v1
	v_max_f32_e32 v48, 0, v0
	v_exp_f32_e64 v0, -v48
	s_or_b64 s[52:53], s[52:53], exec
	s_or_b64 exec, exec, s[16:17]
	v_add_f32_e32 v219, v219, v48
	v_pk_add_f32 v[80:81], v[80:81], v[48:49] op_sel_hi:[1,0] neg_lo:[0,1] neg_hi:[0,1]
	v_pk_add_f32 v[96:97], v[96:97], v[48:49] op_sel_hi:[1,0] neg_lo:[0,1] neg_hi:[0,1]
	v_pk_add_f32 v[82:83], v[82:83], v[48:49] op_sel_hi:[1,0] neg_lo:[0,1] neg_hi:[0,1]
	v_pk_add_f32 v[98:99], v[98:99], v[48:49] op_sel_hi:[1,0] neg_lo:[0,1] neg_hi:[0,1]
	v_pk_add_f32 v[84:85], v[84:85], v[48:49] op_sel_hi:[1,0] neg_lo:[0,1] neg_hi:[0,1]
	v_pk_add_f32 v[100:101], v[100:101], v[48:49] op_sel_hi:[1,0] neg_lo:[0,1] neg_hi:[0,1]
	v_pk_add_f32 v[86:87], v[86:87], v[48:49] op_sel_hi:[1,0] neg_lo:[0,1] neg_hi:[0,1]
	v_pk_add_f32 v[102:103], v[102:103], v[48:49] op_sel_hi:[1,0] neg_lo:[0,1] neg_hi:[0,1]
	v_pk_add_f32 v[88:89], v[88:89], v[48:49] op_sel_hi:[1,0] neg_lo:[0,1] neg_hi:[0,1]
	v_pk_add_f32 v[104:105], v[104:105], v[48:49] op_sel_hi:[1,0] neg_lo:[0,1] neg_hi:[0,1]
	v_pk_add_f32 v[90:91], v[90:91], v[48:49] op_sel_hi:[1,0] neg_lo:[0,1] neg_hi:[0,1]
	v_pk_add_f32 v[106:107], v[106:107], v[48:49] op_sel_hi:[1,0] neg_lo:[0,1] neg_hi:[0,1]
	v_pk_add_f32 v[92:93], v[92:93], v[48:49] op_sel_hi:[1,0] neg_lo:[0,1] neg_hi:[0,1]
	v_pk_add_f32 v[108:109], v[108:109], v[48:49] op_sel_hi:[1,0] neg_lo:[0,1] neg_hi:[0,1]
	v_pk_add_f32 v[94:95], v[94:95], v[48:49] op_sel_hi:[1,0] neg_lo:[0,1] neg_hi:[0,1]
	v_pk_add_f32 v[110:111], v[110:111], v[48:49] op_sel_hi:[1,0] neg_lo:[0,1] neg_hi:[0,1]
	v_xor_b32_e32 v48, 0x80000000, v219
	v_mul_f32_e32 v209, v209, v0
	v_pk_mul_f32 v[46:47], v[46:47], v[0:1] op_sel_hi:[1,0]
	v_pk_mul_f32 v[44:45], v[44:45], v[0:1] op_sel_hi:[1,0]
	v_pk_mul_f32 v[42:43], v[42:43], v[0:1] op_sel_hi:[1,0]
	v_pk_mul_f32 v[40:41], v[40:41], v[0:1] op_sel_hi:[1,0]
	v_pk_mul_f32 v[38:39], v[38:39], v[0:1] op_sel_hi:[1,0]
	v_pk_mul_f32 v[36:37], v[36:37], v[0:1] op_sel_hi:[1,0]
	v_pk_mul_f32 v[34:35], v[34:35], v[0:1] op_sel_hi:[1,0]
	v_pk_mul_f32 v[32:33], v[32:33], v[0:1] op_sel_hi:[1,0]
	v_pk_mul_f32 v[30:31], v[30:31], v[0:1] op_sel_hi:[1,0]
	v_pk_mul_f32 v[28:29], v[28:29], v[0:1] op_sel_hi:[1,0]
	v_pk_mul_f32 v[26:27], v[26:27], v[0:1] op_sel_hi:[1,0]
	v_pk_mul_f32 v[24:25], v[24:25], v[0:1] op_sel_hi:[1,0]
	v_pk_mul_f32 v[22:23], v[22:23], v[0:1] op_sel_hi:[1,0]
	v_pk_mul_f32 v[20:21], v[20:21], v[0:1] op_sel_hi:[1,0]
	v_pk_mul_f32 v[18:19], v[18:19], v[0:1] op_sel_hi:[1,0]
	v_pk_mul_f32 v[16:17], v[16:17], v[0:1] op_sel_hi:[1,0]
	v_mov_b32_e32 v49, v48
	v_mov_b32_e32 v50, v48
	v_mov_b32_e32 v51, v48
	v_mov_b32_e32 v52, v48
	v_mov_b32_e32 v53, v48
	v_mov_b32_e32 v54, v48
	v_mov_b32_e32 v55, v48
	v_mov_b32_e32 v56, v48
	v_mov_b32_e32 v57, v48
	v_mov_b32_e32 v58, v48
	v_mov_b32_e32 v59, v48
	v_mov_b32_e32 v60, v48
	v_mov_b32_e32 v61, v48
	v_mov_b32_e32 v62, v48
	v_mov_b32_e32 v63, v48
	v_mov_b32_e32 v79, v48
	v_mov_b32_e32 v78, v48
	v_mov_b32_e32 v77, v48
	v_mov_b32_e32 v76, v48
	v_mov_b32_e32 v75, v48
	v_mov_b32_e32 v74, v48
	v_mov_b32_e32 v73, v48
	v_mov_b32_e32 v72, v48
	v_mov_b32_e32 v71, v48
	v_mov_b32_e32 v70, v48
	v_mov_b32_e32 v69, v48
	v_mov_b32_e32 v68, v48
	v_mov_b32_e32 v67, v48
	v_mov_b32_e32 v66, v48
	v_mov_b32_e32 v65, v48
	v_mov_b32_e32 v64, v48
	s_branch .LBB0_885

.LBB0_892:
	s_nop 8
	s_xor_b64 s[12:13], s[52:53], -1
	v_max3_f32 v0, v80, v81, v96
	v_max3_f32 v1, v82, v83, v97
	v_max3_f32 v0, v0, v98, v99
	v_max3_f32 v1, v1, v86, v87
	v_max3_f32 v0, v0, v84, v85
	v_max3_f32 v1, v1, v102, v103
	v_max3_f32 v0, v0, v100, v101
	v_max3_f32 v1, v1, v90, v91
	v_max3_f32 v0, v0, v88, v89
	v_max3_f32 v1, v1, v106, v107
	v_max3_f32 v0, v0, v104, v105
	v_max3_f32 v1, v1, v94, v95
	v_max3_f32 v0, v0, v92, v93
	v_max3_f32 v1, v1, v110, v111
	v_max3_f32 v0, v0, v108, v109
	v_max_f32_e32 v0, v0, v1
	v_mov_b32_e32 v1, v0
	s_nop 1
	v_permlane32_swap_b32_e32 v0, v1
	v_max_f32_e32 v1, v0, v1
	v_cmp_lt_f32_e32 vcc, s14, v1
	s_or_b64 s[16:17], vcc, s[12:13]
	s_cbranch_scc0 .LBB0_898
	s_and_saveexec_b64 s[16:17], s[12:13]
	s_xor_b64 s[12:13], exec, s[16:17]
	v_cmp_lg_f32_e64 s[52:53], s5, v1
	s_nop 1
	v_cndmask_b32_e64 v48, 0, v1, s[52:53]
	s_or_saveexec_b64 s[12:13], s[12:13]
	v_mov_b32_e32 v0, 1.0
	s_xor_b64 exec, exec, s[12:13]
	v_max_f32_e32 v0, v1, v1
	v_max_f32_e32 v48, 0, v0
	v_exp_f32_e64 v0, -v48
	s_or_b64 s[52:53], s[52:53], exec
	s_or_b64 exec, exec, s[12:13]
	v_add_f32_e32 v219, v219, v48
	v_pk_add_f32 v[80:81], v[80:81], v[48:49] op_sel_hi:[1,0] neg_lo:[0,1] neg_hi:[0,1]
	v_pk_add_f32 v[96:97], v[96:97], v[48:49] op_sel_hi:[1,0] neg_lo:[0,1] neg_hi:[0,1]
	v_pk_add_f32 v[82:83], v[82:83], v[48:49] op_sel_hi:[1,0] neg_lo:[0,1] neg_hi:[0,1]
	v_pk_add_f32 v[98:99], v[98:99], v[48:49] op_sel_hi:[1,0] neg_lo:[0,1] neg_hi:[0,1]
	v_pk_add_f32 v[84:85], v[84:85], v[48:49] op_sel_hi:[1,0] neg_lo:[0,1] neg_hi:[0,1]
	v_pk_add_f32 v[100:101], v[100:101], v[48:49] op_sel_hi:[1,0] neg_lo:[0,1] neg_hi:[0,1]
	v_pk_add_f32 v[86:87], v[86:87], v[48:49] op_sel_hi:[1,0] neg_lo:[0,1] neg_hi:[0,1]
	v_pk_add_f32 v[102:103], v[102:103], v[48:49] op_sel_hi:[1,0] neg_lo:[0,1] neg_hi:[0,1]
	v_pk_add_f32 v[88:89], v[88:89], v[48:49] op_sel_hi:[1,0] neg_lo:[0,1] neg_hi:[0,1]
	v_pk_add_f32 v[104:105], v[104:105], v[48:49] op_sel_hi:[1,0] neg_lo:[0,1] neg_hi:[0,1]
	v_pk_add_f32 v[90:91], v[90:91], v[48:49] op_sel_hi:[1,0] neg_lo:[0,1] neg_hi:[0,1]
	v_pk_add_f32 v[106:107], v[106:107], v[48:49] op_sel_hi:[1,0] neg_lo:[0,1] neg_hi:[0,1]
	v_pk_add_f32 v[92:93], v[92:93], v[48:49] op_sel_hi:[1,0] neg_lo:[0,1] neg_hi:[0,1]
	v_pk_add_f32 v[108:109], v[108:109], v[48:49] op_sel_hi:[1,0] neg_lo:[0,1] neg_hi:[0,1]
	v_pk_add_f32 v[94:95], v[94:95], v[48:49] op_sel_hi:[1,0] neg_lo:[0,1] neg_hi:[0,1]
	v_pk_add_f32 v[110:111], v[110:111], v[48:49] op_sel_hi:[1,0] neg_lo:[0,1] neg_hi:[0,1]
	v_xor_b32_e32 v48, 0x80000000, v219
	v_mul_f32_e32 v209, v209, v0
	v_pk_mul_f32 v[46:47], v[46:47], v[0:1] op_sel_hi:[1,0]
	v_pk_mul_f32 v[44:45], v[44:45], v[0:1] op_sel_hi:[1,0]
	v_pk_mul_f32 v[42:43], v[42:43], v[0:1] op_sel_hi:[1,0]
	v_pk_mul_f32 v[40:41], v[40:41], v[0:1] op_sel_hi:[1,0]
	v_pk_mul_f32 v[38:39], v[38:39], v[0:1] op_sel_hi:[1,0]
	v_pk_mul_f32 v[36:37], v[36:37], v[0:1] op_sel_hi:[1,0]
	v_pk_mul_f32 v[34:35], v[34:35], v[0:1] op_sel_hi:[1,0]
	v_pk_mul_f32 v[32:33], v[32:33], v[0:1] op_sel_hi:[1,0]
	v_pk_mul_f32 v[30:31], v[30:31], v[0:1] op_sel_hi:[1,0]
	v_pk_mul_f32 v[28:29], v[28:29], v[0:1] op_sel_hi:[1,0]
	v_pk_mul_f32 v[26:27], v[26:27], v[0:1] op_sel_hi:[1,0]
	v_pk_mul_f32 v[24:25], v[24:25], v[0:1] op_sel_hi:[1,0]
	v_pk_mul_f32 v[22:23], v[22:23], v[0:1] op_sel_hi:[1,0]
	v_pk_mul_f32 v[20:21], v[20:21], v[0:1] op_sel_hi:[1,0]
	v_pk_mul_f32 v[18:19], v[18:19], v[0:1] op_sel_hi:[1,0]
	v_pk_mul_f32 v[16:17], v[16:17], v[0:1] op_sel_hi:[1,0]
	v_mov_b32_e32 v49, v48
	v_mov_b32_e32 v50, v48
	v_mov_b32_e32 v51, v48
	v_mov_b32_e32 v52, v48
	v_mov_b32_e32 v53, v48
	v_mov_b32_e32 v54, v48
	v_mov_b32_e32 v55, v48
	v_mov_b32_e32 v56, v48
	v_mov_b32_e32 v57, v48
	v_mov_b32_e32 v58, v48
	v_mov_b32_e32 v59, v48
	v_mov_b32_e32 v60, v48
	v_mov_b32_e32 v61, v48
	v_mov_b32_e32 v62, v48
	v_mov_b32_e32 v63, v48
	v_mov_b32_e32 v79, v48
	v_mov_b32_e32 v78, v48
	v_mov_b32_e32 v77, v48
	v_mov_b32_e32 v76, v48
	v_mov_b32_e32 v75, v48
	v_mov_b32_e32 v74, v48
	v_mov_b32_e32 v73, v48
	v_mov_b32_e32 v72, v48
	v_mov_b32_e32 v71, v48
	v_mov_b32_e32 v70, v48
	v_mov_b32_e32 v69, v48
	v_mov_b32_e32 v68, v48
	v_mov_b32_e32 v67, v48
	v_mov_b32_e32 v66, v48
	v_mov_b32_e32 v65, v48
	v_mov_b32_e32 v64, v48

.LBB0_957:
	s_cmp_lg_u64 s[16:17], exec
	s_cbranch_scc0 .LBB0_959
	s_nop 0
	v_cndmask_b32_e64 v64, v244, v64, s[16:17]
	v_cndmask_b32_e64 v112, v244, v80, s[16:17]
	v_cndmask_b32_e64 v65, v244, v65, s[16:17]
	v_cndmask_b32_e64 v113, v244, v81, s[16:17]
	v_cndmask_b32_e64 v66, v244, v66, s[16:17]
	v_cndmask_b32_e64 v114, v244, v82, s[16:17]
	v_cndmask_b32_e64 v67, v244, v67, s[16:17]
	v_cndmask_b32_e64 v115, v244, v83, s[16:17]
	v_cndmask_b32_e64 v68, v244, v68, s[16:17]
	v_cndmask_b32_e64 v116, v244, v84, s[16:17]
	v_cndmask_b32_e64 v69, v244, v69, s[16:17]
	v_cndmask_b32_e64 v117, v244, v85, s[16:17]
	v_cndmask_b32_e64 v70, v244, v70, s[16:17]
	v_cndmask_b32_e64 v118, v244, v86, s[16:17]
	v_cndmask_b32_e64 v71, v244, v71, s[16:17]
	v_cndmask_b32_e64 v119, v244, v87, s[16:17]
	v_cndmask_b32_e64 v72, v244, v72, s[16:17]
	v_cndmask_b32_e64 v120, v244, v88, s[16:17]
	v_cndmask_b32_e64 v73, v244, v73, s[16:17]
	v_cndmask_b32_e64 v121, v244, v89, s[16:17]
	v_cndmask_b32_e64 v74, v244, v74, s[16:17]
	v_cndmask_b32_e64 v122, v244, v90, s[16:17]
	v_cndmask_b32_e64 v75, v244, v75, s[16:17]
	v_cndmask_b32_e64 v123, v244, v91, s[16:17]
	v_cndmask_b32_e64 v76, v244, v76, s[16:17]
	v_cndmask_b32_e64 v124, v244, v92, s[16:17]
	v_cndmask_b32_e64 v77, v244, v77, s[16:17]
	v_cndmask_b32_e64 v125, v244, v93, s[16:17]
	v_cndmask_b32_e64 v78, v244, v78, s[16:17]
	v_cndmask_b32_e64 v126, v244, v94, s[16:17]
	v_cndmask_b32_e64 v79, v244, v79, s[16:17]
	v_cndmask_b32_e64 v0, v244, v95, s[16:17]
	s_or_b64 s[12:13], s[12:13], exec
	s_branch .LBB0_960

.LBB0_962:
	s_or_b64 exec, exec, s[16:17]
	s_nop 0
	s_xor_b64 s[12:13], s[20:21], -1
	v_max3_f32 v0, v96, v97, v80
	v_max3_f32 v1, v98, v99, v81
	v_max3_f32 v0, v0, v82, v83
	v_max3_f32 v1, v1, v102, v103
	v_max3_f32 v0, v0, v100, v101
	v_max3_f32 v1, v1, v86, v87
	v_max3_f32 v0, v0, v84, v85
	v_max3_f32 v1, v1, v106, v107
	v_max3_f32 v0, v0, v104, v105
	v_max3_f32 v1, v1, v90, v91
	v_max3_f32 v0, v0, v88, v89
	v_max3_f32 v1, v1, v110, v111
	v_max3_f32 v0, v0, v108, v109
	v_max3_f32 v1, v1, v94, v95
	v_max3_f32 v0, v0, v92, v93
	v_max_f32_e32 v0, v0, v1
	v_mov_b32_e32 v1, v0
	s_nop 1
	v_permlane32_swap_b32_e32 v0, v1
	v_max_f32_e32 v1, v0, v1
	v_cmp_lt_f32_e32 vcc, s14, v1
	s_or_b64 s[16:17], vcc, s[12:13]
	s_cbranch_scc0 .LBB0_968
	s_and_saveexec_b64 s[16:17], s[12:13]
	s_xor_b64 s[12:13], exec, s[16:17]
	v_cmp_lg_f32_e64 s[20:21], s5, v1
	s_nop 1
	v_cndmask_b32_e64 v48, 0, v1, s[20:21]
	s_or_saveexec_b64 s[12:13], s[12:13]
	v_mov_b32_e32 v0, 1.0
	s_xor_b64 exec, exec, s[12:13]
	v_max_f32_e32 v0, v1, v1
	v_max_f32_e32 v48, 0, v0
	v_exp_f32_e64 v0, -v48
	s_or_b64 s[20:21], s[20:21], exec
	s_or_b64 exec, exec, s[12:13]
	v_add_f32_e32 v227, v227, v48
	v_xor_b32_e32 v64, 0x80000000, v227
	v_pk_add_f32 v[96:97], v[96:97], v[48:49] op_sel_hi:[1,0] neg_lo:[0,1] neg_hi:[0,1]
	v_pk_add_f32 v[80:81], v[80:81], v[48:49] op_sel_hi:[1,0] neg_lo:[0,1] neg_hi:[0,1]
	v_pk_add_f32 v[98:99], v[98:99], v[48:49] op_sel_hi:[1,0] neg_lo:[0,1] neg_hi:[0,1]
	v_pk_add_f32 v[82:83], v[82:83], v[48:49] op_sel_hi:[1,0] neg_lo:[0,1] neg_hi:[0,1]
	v_pk_add_f32 v[100:101], v[100:101], v[48:49] op_sel_hi:[1,0] neg_lo:[0,1] neg_hi:[0,1]
	v_pk_add_f32 v[84:85], v[84:85], v[48:49] op_sel_hi:[1,0] neg_lo:[0,1] neg_hi:[0,1]
	v_pk_add_f32 v[102:103], v[102:103], v[48:49] op_sel_hi:[1,0] neg_lo:[0,1] neg_hi:[0,1]
	v_pk_add_f32 v[86:87], v[86:87], v[48:49] op_sel_hi:[1,0] neg_lo:[0,1] neg_hi:[0,1]
	v_pk_add_f32 v[104:105], v[104:105], v[48:49] op_sel_hi:[1,0] neg_lo:[0,1] neg_hi:[0,1]
	v_pk_add_f32 v[88:89], v[88:89], v[48:49] op_sel_hi:[1,0] neg_lo:[0,1] neg_hi:[0,1]
	v_pk_add_f32 v[106:107], v[106:107], v[48:49] op_sel_hi:[1,0] neg_lo:[0,1] neg_hi:[0,1]
	v_pk_add_f32 v[90:91], v[90:91], v[48:49] op_sel_hi:[1,0] neg_lo:[0,1] neg_hi:[0,1]
	v_pk_add_f32 v[108:109], v[108:109], v[48:49] op_sel_hi:[1,0] neg_lo:[0,1] neg_hi:[0,1]
	v_pk_add_f32 v[92:93], v[92:93], v[48:49] op_sel_hi:[1,0] neg_lo:[0,1] neg_hi:[0,1]
	v_pk_add_f32 v[110:111], v[110:111], v[48:49] op_sel_hi:[1,0] neg_lo:[0,1] neg_hi:[0,1]
	v_pk_add_f32 v[94:95], v[94:95], v[48:49] op_sel_hi:[1,0] neg_lo:[0,1] neg_hi:[0,1]
	v_mul_f32_e32 v226, v226, v0
	v_pk_mul_f32 v[46:47], v[46:47], v[0:1] op_sel_hi:[1,0]
	v_pk_mul_f32 v[44:45], v[44:45], v[0:1] op_sel_hi:[1,0]
	v_pk_mul_f32 v[42:43], v[42:43], v[0:1] op_sel_hi:[1,0]
	v_pk_mul_f32 v[40:41], v[40:41], v[0:1] op_sel_hi:[1,0]
	v_pk_mul_f32 v[38:39], v[38:39], v[0:1] op_sel_hi:[1,0]
	v_pk_mul_f32 v[36:37], v[36:37], v[0:1] op_sel_hi:[1,0]
	v_pk_mul_f32 v[34:35], v[34:35], v[0:1] op_sel_hi:[1,0]
	v_pk_mul_f32 v[32:33], v[32:33], v[0:1] op_sel_hi:[1,0]
	v_pk_mul_f32 v[30:31], v[30:31], v[0:1] op_sel_hi:[1,0]
	v_pk_mul_f32 v[28:29], v[28:29], v[0:1] op_sel_hi:[1,0]
	v_pk_mul_f32 v[26:27], v[26:27], v[0:1] op_sel_hi:[1,0]
	v_pk_mul_f32 v[24:25], v[24:25], v[0:1] op_sel_hi:[1,0]
	v_pk_mul_f32 v[22:23], v[22:23], v[0:1] op_sel_hi:[1,0]
	v_pk_mul_f32 v[20:21], v[20:21], v[0:1] op_sel_hi:[1,0]
	v_pk_mul_f32 v[18:19], v[18:19], v[0:1] op_sel_hi:[1,0]
	v_pk_mul_f32 v[16:17], v[16:17], v[0:1] op_sel_hi:[1,0]
	v_mov_b32_e32 v65, v64
	v_mov_b32_e32 v66, v64
	v_mov_b32_e32 v67, v64
	v_mov_b32_e32 v68, v64
	v_mov_b32_e32 v69, v64
	v_mov_b32_e32 v70, v64
	v_mov_b32_e32 v71, v64
	v_mov_b32_e32 v72, v64
	v_mov_b32_e32 v73, v64
	v_mov_b32_e32 v74, v64
	v_mov_b32_e32 v75, v64
	v_mov_b32_e32 v76, v64
	v_mov_b32_e32 v77, v64
	v_mov_b32_e32 v78, v64
	v_mov_b32_e32 v79, v64
	v_mov_b32_e32 v63, v64
	v_mov_b32_e32 v62, v64
	v_mov_b32_e32 v61, v64
	v_mov_b32_e32 v60, v64
	v_mov_b32_e32 v59, v64
	v_mov_b32_e32 v58, v64
	v_mov_b32_e32 v57, v64
	v_mov_b32_e32 v56, v64
	v_mov_b32_e32 v55, v64
	v_mov_b32_e32 v54, v64
	v_mov_b32_e32 v53, v64
	v_mov_b32_e32 v52, v64
	v_mov_b32_e32 v51, v64
	v_mov_b32_e32 v50, v64
	v_mov_b32_e32 v49, v64
	v_mov_b32_e32 v48, v64
	s_branch .LBB0_969

.LBB0_977:
	s_cmp_lg_u64 s[16:17], exec
	s_cbranch_scc0 .LBB0_979
	s_nop 0
	v_cndmask_b32_e64 v96, v244, v96, s[16:17]
	v_cndmask_b32_e64 v112, v244, v64, s[16:17]
	v_cndmask_b32_e64 v97, v244, v97, s[16:17]
	v_cndmask_b32_e64 v113, v244, v65, s[16:17]
	v_cndmask_b32_e64 v98, v244, v98, s[16:17]
	v_cndmask_b32_e64 v114, v244, v66, s[16:17]
	v_cndmask_b32_e64 v99, v244, v99, s[16:17]
	v_cndmask_b32_e64 v115, v244, v67, s[16:17]
	v_cndmask_b32_e64 v100, v244, v100, s[16:17]
	v_cndmask_b32_e64 v116, v244, v68, s[16:17]
	v_cndmask_b32_e64 v101, v244, v101, s[16:17]
	v_cndmask_b32_e64 v117, v244, v69, s[16:17]
	v_cndmask_b32_e64 v102, v244, v102, s[16:17]
	v_cndmask_b32_e64 v118, v244, v70, s[16:17]
	v_cndmask_b32_e64 v103, v244, v103, s[16:17]
	v_cndmask_b32_e64 v119, v244, v71, s[16:17]
	v_cndmask_b32_e64 v104, v244, v104, s[16:17]
	v_cndmask_b32_e64 v120, v244, v72, s[16:17]
	v_cndmask_b32_e64 v105, v244, v105, s[16:17]
	v_cndmask_b32_e64 v121, v244, v73, s[16:17]
	v_cndmask_b32_e64 v106, v244, v106, s[16:17]
	v_cndmask_b32_e64 v122, v244, v74, s[16:17]
	v_cndmask_b32_e64 v107, v244, v107, s[16:17]
	v_cndmask_b32_e64 v123, v244, v75, s[16:17]
	v_cndmask_b32_e64 v108, v244, v108, s[16:17]
	v_cndmask_b32_e64 v124, v244, v76, s[16:17]
	v_cndmask_b32_e64 v109, v244, v109, s[16:17]
	v_cndmask_b32_e64 v125, v244, v77, s[16:17]
	v_cndmask_b32_e64 v110, v244, v110, s[16:17]
	v_cndmask_b32_e64 v126, v244, v78, s[16:17]
	v_cndmask_b32_e64 v111, v244, v111, s[16:17]
	v_cndmask_b32_e64 v0, v244, v79, s[16:17]
	s_or_b64 s[24:25], s[24:25], exec
	s_branch .LBB0_980

.LBB0_982:
	s_or_b64 exec, exec, s[16:17]
	s_nop 0
	s_xor_b64 s[16:17], s[20:21], -1
	v_max3_f32 v0, v80, v81, v64
	v_max3_f32 v1, v82, v83, v65
	v_max3_f32 v0, v0, v66, v67
	v_max3_f32 v1, v1, v86, v87
	v_max3_f32 v0, v0, v84, v85
	v_max3_f32 v1, v1, v70, v71
	v_max3_f32 v0, v0, v68, v69
	v_max3_f32 v1, v1, v90, v91
	v_max3_f32 v0, v0, v88, v89
	v_max3_f32 v1, v1, v74, v75
	v_max3_f32 v0, v0, v72, v73
	v_max3_f32 v1, v1, v94, v95
	v_max3_f32 v0, v0, v92, v93
	v_max3_f32 v1, v1, v78, v79
	v_max3_f32 v0, v0, v76, v77
	v_max_f32_e32 v0, v0, v1
	v_mov_b32_e32 v1, v0
	s_nop 1
	v_permlane32_swap_b32_e32 v0, v1
	v_max_f32_e32 v1, v0, v1
	v_cmp_lt_f32_e32 vcc, s14, v1
	s_or_b64 s[24:25], vcc, s[16:17]
	s_cbranch_scc0 .LBB0_988
	s_and_saveexec_b64 s[24:25], s[16:17]
	s_xor_b64 s[16:17], exec, s[24:25]
	v_cmp_lg_f32_e64 s[20:21], s5, v1
	s_nop 1
	v_cndmask_b32_e64 v48, 0, v1, s[20:21]
	s_or_saveexec_b64 s[16:17], s[16:17]
	v_mov_b32_e32 v0, 1.0
	s_xor_b64 exec, exec, s[16:17]
	v_max_f32_e32 v0, v1, v1
	v_max_f32_e32 v48, 0, v0
	v_exp_f32_e64 v0, -v48
	s_or_b64 s[20:21], s[20:21], exec
	s_or_b64 exec, exec, s[16:17]
	v_add_f32_e32 v227, v227, v48
	v_xor_b32_e32 v63, 0x80000000, v227
	v_pk_add_f32 v[80:81], v[80:81], v[48:49] op_sel_hi:[1,0] neg_lo:[0,1] neg_hi:[0,1]
	v_pk_add_f32 v[64:65], v[64:65], v[48:49] op_sel_hi:[1,0] neg_lo:[0,1] neg_hi:[0,1]
	v_pk_add_f32 v[82:83], v[82:83], v[48:49] op_sel_hi:[1,0] neg_lo:[0,1] neg_hi:[0,1]
	v_pk_add_f32 v[66:67], v[66:67], v[48:49] op_sel_hi:[1,0] neg_lo:[0,1] neg_hi:[0,1]
	v_pk_add_f32 v[84:85], v[84:85], v[48:49] op_sel_hi:[1,0] neg_lo:[0,1] neg_hi:[0,1]
	v_pk_add_f32 v[68:69], v[68:69], v[48:49] op_sel_hi:[1,0] neg_lo:[0,1] neg_hi:[0,1]
	v_pk_add_f32 v[86:87], v[86:87], v[48:49] op_sel_hi:[1,0] neg_lo:[0,1] neg_hi:[0,1]
	v_pk_add_f32 v[70:71], v[70:71], v[48:49] op_sel_hi:[1,0] neg_lo:[0,1] neg_hi:[0,1]
	v_pk_add_f32 v[88:89], v[88:89], v[48:49] op_sel_hi:[1,0] neg_lo:[0,1] neg_hi:[0,1]
	v_pk_add_f32 v[72:73], v[72:73], v[48:49] op_sel_hi:[1,0] neg_lo:[0,1] neg_hi:[0,1]
	v_pk_add_f32 v[90:91], v[90:91], v[48:49] op_sel_hi:[1,0] neg_lo:[0,1] neg_hi:[0,1]
	v_pk_add_f32 v[74:75], v[74:75], v[48:49] op_sel_hi:[1,0] neg_lo:[0,1] neg_hi:[0,1]
	v_pk_add_f32 v[92:93], v[92:93], v[48:49] op_sel_hi:[1,0] neg_lo:[0,1] neg_hi:[0,1]
	v_pk_add_f32 v[76:77], v[76:77], v[48:49] op_sel_hi:[1,0] neg_lo:[0,1] neg_hi:[0,1]
	v_pk_add_f32 v[94:95], v[94:95], v[48:49] op_sel_hi:[1,0] neg_lo:[0,1] neg_hi:[0,1]
	v_pk_add_f32 v[78:79], v[78:79], v[48:49] op_sel_hi:[1,0] neg_lo:[0,1] neg_hi:[0,1]
	v_mul_f32_e32 v226, v226, v0
	v_pk_mul_f32 v[46:47], v[46:47], v[0:1] op_sel_hi:[1,0]
	v_pk_mul_f32 v[44:45], v[44:45], v[0:1] op_sel_hi:[1,0]
	v_pk_mul_f32 v[42:43], v[42:43], v[0:1] op_sel_hi:[1,0]
	v_pk_mul_f32 v[40:41], v[40:41], v[0:1] op_sel_hi:[1,0]
	v_pk_mul_f32 v[38:39], v[38:39], v[0:1] op_sel_hi:[1,0]
	v_pk_mul_f32 v[36:37], v[36:37], v[0:1] op_sel_hi:[1,0]
	v_pk_mul_f32 v[34:35], v[34:35], v[0:1] op_sel_hi:[1,0]
	v_pk_mul_f32 v[32:33], v[32:33], v[0:1] op_sel_hi:[1,0]
	v_pk_mul_f32 v[30:31], v[30:31], v[0:1] op_sel_hi:[1,0]
	v_pk_mul_f32 v[28:29], v[28:29], v[0:1] op_sel_hi:[1,0]
	v_pk_mul_f32 v[26:27], v[26:27], v[0:1] op_sel_hi:[1,0]
	v_pk_mul_f32 v[24:25], v[24:25], v[0:1] op_sel_hi:[1,0]
	v_pk_mul_f32 v[22:23], v[22:23], v[0:1] op_sel_hi:[1,0]
	v_pk_mul_f32 v[20:21], v[20:21], v[0:1] op_sel_hi:[1,0]
	v_pk_mul_f32 v[18:19], v[18:19], v[0:1] op_sel_hi:[1,0]
	v_pk_mul_f32 v[16:17], v[16:17], v[0:1] op_sel_hi:[1,0]
	v_mov_b32_e32 v62, v63
	v_mov_b32_e32 v61, v63
	v_mov_b32_e32 v60, v63
	v_mov_b32_e32 v59, v63
	v_mov_b32_e32 v58, v63
	v_mov_b32_e32 v57, v63
	v_mov_b32_e32 v56, v63
	v_mov_b32_e32 v55, v63
	v_mov_b32_e32 v54, v63
	v_mov_b32_e32 v53, v63
	v_mov_b32_e32 v52, v63
	v_mov_b32_e32 v51, v63
	v_mov_b32_e32 v50, v63
	v_mov_b32_e32 v49, v63
	v_mov_b32_e32 v48, v63

.LBB0_999:
	ds_read_b128 v[4:7], v239
	ds_read_b128 v[8:11], v239 offset:32
	ds_read_b128 v[12:15], v239 offset:4608
	ds_read_b128 v[64:67], v239 offset:4640
	ds_read_b128 v[68:71], v239 offset:64
	ds_read_b128 v[72:75], v239 offset:96
	ds_read_b128 v[76:79], v239 offset:4672
	ds_read_b128 v[112:115], v239 offset:4704
	s_lshl_b32 s2, s2, 6
	s_setprio 1
	s_waitcnt lgkmcnt(7)
	v_mfma_f32_32x32x16_bf16 v[80:95], v[4:7], v[132:135], v[48:63]
	s_waitcnt lgkmcnt(5)
	v_mfma_f32_32x32x16_bf16 v[96:111], v[12:15], v[132:135], v[48:63]
	s_setprio 0
	v_mfma_f32_32x32x16_bf16 v[80:95], v[8:11], v[136:139], v[80:95]
	ds_read_b64_tr_b16 v[4:5], v235 offset:18432
	ds_read_b64_tr_b16 v[6:7], v235 offset:19968
	ds_read_b64_tr_b16 v[10:11], v235 offset:20032
	ds_read_b64_tr_b16 v[8:9], v235 offset:18496
	ds_read_b64_tr_b16 v[12:13], v235 offset:21504
	ds_read_b64_tr_b16 v[14:15], v235 offset:23040
	ds_read_b64_tr_b16 v[166:167], v235 offset:23104
	ds_read_b64_tr_b16 v[164:165], v235 offset:21568
	ds_read_b64_tr_b16 v[168:169], v235 offset:24576
	ds_read_b64_tr_b16 v[170:171], v235 offset:26112
	ds_read_b64_tr_b16 v[174:175], v235 offset:26176
	ds_read_b64_tr_b16 v[172:173], v235 offset:24640
	ds_read_b64_tr_b16 v[176:177], v235 offset:27648
	ds_read_b64_tr_b16 v[178:179], v235 offset:29184
	ds_read_b64_tr_b16 v[182:183], v235 offset:29248
	ds_read_b64_tr_b16 v[180:181], v235 offset:27712
	s_waitcnt lgkmcnt(14)
	v_mfma_f32_32x32x16_bf16 v[96:111], v[64:67], v[136:139], v[96:111]
	v_mfma_f32_32x32x16_bf16 v[80:95], v[68:71], v[140:143], v[80:95]
	v_mfma_f32_32x32x16_bf16 v[96:111], v[76:79], v[140:143], v[96:111]
	v_mfma_f32_32x32x16_bf16 v[80:95], v[72:75], v[144:147], v[80:95]
	v_mfma_f32_32x32x16_bf16 v[96:111], v[112:115], v[144:147], v[96:111]
	s_or_b32 s16, s2, 63
	v_cmp_ge_i32_e32 vcc, s2, v226
	v_cmp_le_u32_e64 s[16:17], s16, v246
	s_and_b64 s[16:17], vcc, s[16:17]
	s_nop 0
	s_cmp_eq_u64 s[16:17], exec
	s_cbranch_scc1 .LBB0_1003
	v_or_b32_e32 v0, s2, v237
	v_or_b32_e32 v1, 32, v0
	v_cmp_lt_i32_e64 s[18:19], v1, v226
	v_cmp_gt_u32_e64 s[20:21], v1, v246
	s_or_b64 s[18:19], s[18:19], s[20:21]
	v_or_b32_e32 v1, 1, v0
	v_cndmask_b32_e64 v96, v96, v244, s[18:19]
	v_cmp_ge_i32_e64 s[18:19], v1, v226
	v_or_b32_e32 v1, 33, v0
	v_cmp_lt_i32_e64 s[22:23], v1, v226
	v_cmp_gt_u32_e64 s[24:25], v1, v246
	s_or_b64 s[22:23], s[22:23], s[24:25]
	v_or_b32_e32 v1, 2, v0
	v_cndmask_b32_e64 v97, v97, v244, s[22:23]
	v_cmp_ge_i32_e64 s[22:23], v1, v226
	v_cmp_le_u32_e64 s[24:25], v1, v246
	v_or_b32_e32 v1, 34, v0
	v_cmp_lt_i32_e64 s[26:27], v1, v226
	v_cmp_gt_u32_e64 s[28:29], v1, v246
	v_or_b32_e32 v1, s2, v236
	s_or_b64 s[26:27], s[26:27], s[28:29]
	v_or_b32_e32 v3, 3, v1
	v_cndmask_b32_e64 v98, v98, v244, s[26:27]
	v_cmp_ge_i32_e64 s[26:27], v3, v226
	v_cmp_le_u32_e64 s[28:29], v3, v246
	v_or_b32_e32 v3, 35, v1
	v_cmp_lt_i32_e64 s[30:31], v3, v226
	v_cmp_gt_u32_e64 s[34:35], v3, v246
	s_or_b64 s[30:31], s[30:31], s[34:35]
	v_or_b32_e32 v3, 8, v0
	v_cndmask_b32_e64 v99, v99, v244, s[30:31]
	v_cmp_ge_i32_e64 s[30:31], v3, v226
	v_cmp_le_u32_e64 s[34:35], v3, v246
	v_or_b32_e32 v3, 40, v0
	v_cmp_lt_i32_e64 s[36:37], v3, v226
	v_cmp_gt_u32_e64 s[38:39], v3, v246
	s_or_b64 s[36:37], s[36:37], s[38:39]
	v_or_b32_e32 v3, 9, v0
	v_cndmask_b32_e64 v100, v100, v244, s[36:37]
	v_cmp_ge_i32_e64 s[36:37], v3, v226
	v_cmp_le_u32_e64 s[38:39], v3, v246
	v_or_b32_e32 v3, 41, v0
	v_cmp_lt_i32_e64 s[40:41], v3, v226
	v_cmp_gt_u32_e64 s[42:43], v3, v246
	s_or_b64 s[40:41], s[40:41], s[42:43]
	v_or_b32_e32 v3, 10, v0
	v_cndmask_b32_e64 v101, v101, v244, s[40:41]
	v_cmp_ge_i32_e64 s[40:41], v3, v226
	v_cmp_le_u32_e64 s[42:43], v3, v246
	v_or_b32_e32 v3, 42, v0
	v_cmp_lt_i32_e64 s[44:45], v3, v226
	v_cmp_gt_u32_e64 s[46:47], v3, v246
	s_or_b64 s[44:45], s[44:45], s[46:47]
	v_or_b32_e32 v3, 11, v1
	v_cndmask_b32_e64 v102, v102, v244, s[44:45]
	v_cmp_ge_i32_e64 s[44:45], v3, v226
	v_cmp_le_u32_e64 s[46:47], v3, v246
	v_or_b32_e32 v3, 43, v1
	v_cmp_lt_i32_e64 s[48:49], v3, v226
	v_cmp_gt_u32_e64 s[50:51], v3, v246
	s_or_b64 s[48:49], s[48:49], s[50:51]
	v_or_b32_e32 v3, 16, v0
	v_cndmask_b32_e64 v103, v103, v244, s[48:49]
	v_cmp_ge_i32_e64 s[48:49], v3, v226
	v_cmp_le_u32_e64 s[50:51], v3, v246
	v_or_b32_e32 v3, 48, v0
	v_cmp_lt_i32_e64 s[52:53], v3, v226
	v_cmp_gt_u32_e64 s[54:55], v3, v246
	s_or_b64 s[52:53], s[52:53], s[54:55]
	v_or_b32_e32 v3, 17, v0
	v_cndmask_b32_e64 v104, v104, v244, s[52:53]
	v_cmp_ge_i32_e64 s[52:53], v3, v226
	v_cmp_le_u32_e64 s[54:55], v3, v246
	v_or_b32_e32 v3, 49, v0
	v_cmp_lt_i32_e64 s[56:57], v3, v226
	v_cmp_gt_u32_e64 s[58:59], v3, v246
	s_or_b64 s[56:57], s[56:57], s[58:59]
	v_or_b32_e32 v3, 18, v0
	v_cndmask_b32_e64 v105, v105, v244, s[56:57]
	v_cmp_ge_i32_e64 s[56:57], v3, v226
	v_cmp_le_u32_e64 s[58:59], v3, v246
	v_or_b32_e32 v3, 50, v0
	v_cmp_lt_i32_e64 s[60:61], v3, v226
	v_cmp_gt_u32_e64 s[62:63], v3, v246
	s_or_b64 s[60:61], s[60:61], s[62:63]
	v_or_b32_e32 v3, 19, v1
	v_cndmask_b32_e64 v106, v106, v244, s[60:61]
	v_cmp_ge_i32_e64 s[60:61], v3, v226
	v_cmp_le_u32_e64 s[62:63], v3, v246
	v_or_b32_e32 v3, 51, v1
	v_cmp_lt_i32_e64 s[64:65], v3, v226
	v_cmp_gt_u32_e64 s[66:67], v3, v246
	s_or_b64 s[64:65], s[64:65], s[66:67]
	v_or_b32_e32 v3, 24, v0
	v_cndmask_b32_e64 v107, v107, v244, s[64:65]
	v_cmp_ge_i32_e64 s[64:65], v3, v226
	v_cmp_le_u32_e64 s[66:67], v3, v246
	v_or_b32_e32 v3, 56, v0
	v_cmp_lt_i32_e64 s[68:69], v3, v226
	v_cmp_gt_u32_e64 s[70:71], v3, v246
	s_or_b64 s[68:69], s[68:69], s[70:71]
	v_or_b32_e32 v3, 25, v0
	v_cndmask_b32_e64 v108, v108, v244, s[68:69]
	v_cmp_ge_i32_e64 s[68:69], v3, v226
	v_cmp_le_u32_e64 s[70:71], v3, v246
	v_or_b32_e32 v3, 57, v0
	v_cmp_ge_i32_e32 vcc, v0, v226
	v_cmp_le_u32_e64 s[16:17], v0, v246
	v_cmp_lt_u32_e64 s[20:21], v0, v246
	v_cmp_lt_i32_e64 s[72:73], v3, v226
	v_cmp_gt_u32_e64 s[74:75], v3, v246
	v_or_b32_e32 v3, 26, v0
	v_or_b32_e32 v0, 58, v0
	v_cmp_lt_i32_e64 s[76:77], v0, v226
	v_cmp_gt_u32_e64 s[78:79], v0, v246
	s_or_b64 s[76:77], s[76:77], s[78:79]
	v_or_b32_e32 v0, 27, v1
	v_cndmask_b32_e64 v110, v110, v244, s[76:77]
	v_cmp_ge_i32_e64 s[76:77], v0, v226
	v_cmp_le_u32_e64 s[78:79], v0, v246
	v_or_b32_e32 v0, 59, v1
	s_or_b64 s[72:73], s[72:73], s[74:75]
	v_cmp_lt_i32_e64 s[82:83], v0, v226
	v_cmp_gt_u32_e64 s[84:85], v0, v246
	v_cndmask_b32_e64 v109, v109, v244, s[72:73]
	v_cmp_ge_i32_e64 s[72:73], v3, v226
	v_cmp_le_u32_e64 s[74:75], v3, v246
	s_or_b64 s[84:85], s[82:83], s[84:85]
	s_and_saveexec_b64 s[82:83], s[84:85]
	v_mov_b32_e32 v111, s5
	s_or_b64 exec, exec, s[82:83]
	s_and_b64 vcc, vcc, s[16:17]
	v_cndmask_b32_e32 v80, v244, v80, vcc
	s_and_b64 vcc, s[20:21], s[18:19]
	v_cndmask_b32_e32 v81, v244, v81, vcc
	s_and_b64 vcc, s[22:23], s[24:25]
	v_cndmask_b32_e32 v82, v244, v82, vcc
	s_and_b64 vcc, s[26:27], s[28:29]
	v_cndmask_b32_e32 v83, v244, v83, vcc
	s_and_b64 vcc, s[30:31], s[34:35]
	v_cndmask_b32_e32 v84, v244, v84, vcc
	s_and_b64 vcc, s[36:37], s[38:39]
	v_cndmask_b32_e32 v85, v244, v85, vcc
	s_and_b64 vcc, s[40:41], s[42:43]
	v_cndmask_b32_e32 v86, v244, v86, vcc
	s_and_b64 vcc, s[44:45], s[46:47]
	v_cndmask_b32_e32 v87, v244, v87, vcc
	s_and_b64 vcc, s[48:49], s[50:51]
	v_cndmask_b32_e32 v88, v244, v88, vcc
	s_and_b64 vcc, s[52:53], s[54:55]
	v_cndmask_b32_e32 v89, v244, v89, vcc
	s_and_b64 vcc, s[56:57], s[58:59]
	v_cndmask_b32_e32 v90, v244, v90, vcc
	s_and_b64 vcc, s[60:61], s[62:63]
	v_cndmask_b32_e32 v91, v244, v91, vcc
	s_and_b64 vcc, s[64:65], s[66:67]
	v_cndmask_b32_e32 v92, v244, v92, vcc
	s_and_b64 vcc, s[68:69], s[70:71]
	v_cndmask_b32_e32 v93, v244, v93, vcc
	s_and_b64 vcc, s[72:73], s[74:75]
	v_cndmask_b32_e32 v94, v244, v94, vcc
	s_and_b64 vcc, s[76:77], s[78:79]
	v_cndmask_b32_e32 v95, v244, v95, vcc
.LBB0_1003:
	s_nop 3
	s_xor_b64 s[16:17], s[94:95], -1
	v_max3_f32 v0, v80, v81, v96
	v_max3_f32 v1, v82, v83, v97
	v_max3_f32 v0, v0, v98, v99
	v_max3_f32 v1, v1, v86, v87
	v_max3_f32 v0, v0, v84, v85
	v_max3_f32 v1, v1, v102, v103
	v_max3_f32 v0, v0, v100, v101
	v_max3_f32 v1, v1, v90, v91
	v_max3_f32 v0, v0, v88, v89
	v_max3_f32 v1, v1, v106, v107
	v_max3_f32 v0, v0, v104, v105
	v_max3_f32 v1, v1, v94, v95
	v_max3_f32 v0, v0, v92, v93
	v_max3_f32 v1, v1, v110, v111
	v_max3_f32 v0, v0, v108, v109
	v_max_f32_e32 v0, v0, v1
	v_mov_b32_e32 v1, v0
	s_nop 1
	v_permlane32_swap_b32_e32 v0, v1
	v_max_f32_e32 v1, v0, v1
	v_cmp_lt_f32_e32 vcc, s14, v1
	s_or_b64 s[18:19], vcc, s[16:17]
	s_cbranch_scc0 .LBB0_1009
	s_and_saveexec_b64 s[18:19], s[16:17]
	s_xor_b64 s[16:17], exec, s[18:19]
	v_cmp_lg_f32_e64 s[94:95], s5, v1
	s_nop 1
	v_cndmask_b32_e64 v48, 0, v1, s[94:95]
	s_or_saveexec_b64 s[16:17], s[16:17]
	v_mov_b32_e32 v0, 1.0
	s_xor_b64 exec, exec, s[16:17]
	v_max_f32_e32 v0, v1, v1
	v_max_f32_e32 v48, 0, v0
	v_exp_f32_e64 v0, -v48
	s_or_b64 s[94:95], s[94:95], exec
	s_or_b64 exec, exec, s[16:17]
	v_add_f32_e32 v248, v248, v48
	v_xor_b32_e32 v64, 0x80000000, v248
	v_pk_add_f32 v[80:81], v[80:81], v[48:49] op_sel_hi:[1,0] neg_lo:[0,1] neg_hi:[0,1]
	v_pk_add_f32 v[96:97], v[96:97], v[48:49] op_sel_hi:[1,0] neg_lo:[0,1] neg_hi:[0,1]
	v_pk_add_f32 v[82:83], v[82:83], v[48:49] op_sel_hi:[1,0] neg_lo:[0,1] neg_hi:[0,1]
	v_pk_add_f32 v[98:99], v[98:99], v[48:49] op_sel_hi:[1,0] neg_lo:[0,1] neg_hi:[0,1]
	v_pk_add_f32 v[84:85], v[84:85], v[48:49] op_sel_hi:[1,0] neg_lo:[0,1] neg_hi:[0,1]
	v_pk_add_f32 v[100:101], v[100:101], v[48:49] op_sel_hi:[1,0] neg_lo:[0,1] neg_hi:[0,1]
	v_pk_add_f32 v[86:87], v[86:87], v[48:49] op_sel_hi:[1,0] neg_lo:[0,1] neg_hi:[0,1]
	v_pk_add_f32 v[102:103], v[102:103], v[48:49] op_sel_hi:[1,0] neg_lo:[0,1] neg_hi:[0,1]
	v_pk_add_f32 v[88:89], v[88:89], v[48:49] op_sel_hi:[1,0] neg_lo:[0,1] neg_hi:[0,1]
	v_pk_add_f32 v[104:105], v[104:105], v[48:49] op_sel_hi:[1,0] neg_lo:[0,1] neg_hi:[0,1]
	v_pk_add_f32 v[90:91], v[90:91], v[48:49] op_sel_hi:[1,0] neg_lo:[0,1] neg_hi:[0,1]
	v_pk_add_f32 v[106:107], v[106:107], v[48:49] op_sel_hi:[1,0] neg_lo:[0,1] neg_hi:[0,1]
	v_pk_add_f32 v[92:93], v[92:93], v[48:49] op_sel_hi:[1,0] neg_lo:[0,1] neg_hi:[0,1]
	v_pk_add_f32 v[108:109], v[108:109], v[48:49] op_sel_hi:[1,0] neg_lo:[0,1] neg_hi:[0,1]
	v_pk_add_f32 v[94:95], v[94:95], v[48:49] op_sel_hi:[1,0] neg_lo:[0,1] neg_hi:[0,1]
	v_pk_add_f32 v[110:111], v[110:111], v[48:49] op_sel_hi:[1,0] neg_lo:[0,1] neg_hi:[0,1]
	v_mul_f32_e32 v222, v222, v0
	v_pk_mul_f32 v[46:47], v[46:47], v[0:1] op_sel_hi:[1,0]
	v_pk_mul_f32 v[44:45], v[44:45], v[0:1] op_sel_hi:[1,0]
	v_pk_mul_f32 v[42:43], v[42:43], v[0:1] op_sel_hi:[1,0]
	v_pk_mul_f32 v[40:41], v[40:41], v[0:1] op_sel_hi:[1,0]
	v_pk_mul_f32 v[38:39], v[38:39], v[0:1] op_sel_hi:[1,0]
	v_pk_mul_f32 v[36:37], v[36:37], v[0:1] op_sel_hi:[1,0]
	v_pk_mul_f32 v[34:35], v[34:35], v[0:1] op_sel_hi:[1,0]
	v_pk_mul_f32 v[32:33], v[32:33], v[0:1] op_sel_hi:[1,0]
	v_pk_mul_f32 v[30:31], v[30:31], v[0:1] op_sel_hi:[1,0]
	v_pk_mul_f32 v[28:29], v[28:29], v[0:1] op_sel_hi:[1,0]
	v_pk_mul_f32 v[26:27], v[26:27], v[0:1] op_sel_hi:[1,0]
	v_pk_mul_f32 v[24:25], v[24:25], v[0:1] op_sel_hi:[1,0]
	v_pk_mul_f32 v[22:23], v[22:23], v[0:1] op_sel_hi:[1,0]
	v_pk_mul_f32 v[20:21], v[20:21], v[0:1] op_sel_hi:[1,0]
	v_pk_mul_f32 v[18:19], v[18:19], v[0:1] op_sel_hi:[1,0]
	v_pk_mul_f32 v[16:17], v[16:17], v[0:1] op_sel_hi:[1,0]
	v_mov_b32_e32 v65, v64
	v_mov_b32_e32 v66, v64
	v_mov_b32_e32 v67, v64
	v_mov_b32_e32 v68, v64
	v_mov_b32_e32 v69, v64
	v_mov_b32_e32 v70, v64
	v_mov_b32_e32 v71, v64
	v_mov_b32_e32 v72, v64
	v_mov_b32_e32 v73, v64
	v_mov_b32_e32 v74, v64
	v_mov_b32_e32 v75, v64
	v_mov_b32_e32 v76, v64
	v_mov_b32_e32 v77, v64
	v_mov_b32_e32 v78, v64
	v_mov_b32_e32 v79, v64
	v_mov_b32_e32 v63, v64
	v_mov_b32_e32 v62, v64
	v_mov_b32_e32 v61, v64
	v_mov_b32_e32 v60, v64
	v_mov_b32_e32 v59, v64
	v_mov_b32_e32 v58, v64
	v_mov_b32_e32 v57, v64
	v_mov_b32_e32 v56, v64
	v_mov_b32_e32 v55, v64
	v_mov_b32_e32 v54, v64
	v_mov_b32_e32 v53, v64
	v_mov_b32_e32 v52, v64
	v_mov_b32_e32 v51, v64
	v_mov_b32_e32 v50, v64
	v_mov_b32_e32 v49, v64
	v_mov_b32_e32 v48, v64
	s_branch .LBB0_1010

.LBB0_1013:
	ds_read_b128 v[4:7], v239 offset:9216
	ds_read_b128 v[8:11], v239 offset:9248
	ds_read_b128 v[12:15], v239 offset:13824
	ds_read_b128 v[96:99], v239 offset:13856
	ds_read_b128 v[100:103], v239 offset:9280
	ds_read_b128 v[104:107], v239 offset:9312
	ds_read_b128 v[108:111], v239 offset:13888
	ds_read_b128 v[116:119], v239 offset:13920
	s_lshl_b32 s12, s33, 6
	s_setprio 1
	s_waitcnt lgkmcnt(7)
	v_mfma_f32_32x32x16_bf16 v[80:95], v[4:7], v[132:135], v[64:79]
	s_waitcnt lgkmcnt(5)
	v_mfma_f32_32x32x16_bf16 v[64:79], v[12:15], v[132:135], v[64:79]
	s_setprio 0
	v_mfma_f32_32x32x16_bf16 v[80:95], v[8:11], v[136:139], v[80:95]
	s_waitcnt lgkmcnt(4)
	v_mfma_f32_32x32x16_bf16 v[64:79], v[96:99], v[136:139], v[64:79]
	ds_read_b64_tr_b16 v[4:5], v235 offset:30720
	ds_read_b64_tr_b16 v[6:7], v235 offset:32256
	ds_read_b64_tr_b16 v[10:11], v235 offset:32320
	ds_read_b64_tr_b16 v[8:9], v235 offset:30784
	ds_read_b64_tr_b16 v[12:13], v235 offset:33792
	ds_read_b64_tr_b16 v[14:15], v235 offset:35328
	ds_read_b64_tr_b16 v[98:99], v235 offset:35392
	ds_read_b64_tr_b16 v[96:97], v235 offset:33856
	s_waitcnt lgkmcnt(11)
	v_mfma_f32_32x32x16_bf16 v[80:95], v[100:103], v[140:143], v[80:95]
	s_waitcnt lgkmcnt(9)
	v_mfma_f32_32x32x16_bf16 v[64:79], v[108:111], v[140:143], v[64:79]
	v_mfma_f32_32x32x16_bf16 v[80:95], v[104:107], v[144:147], v[80:95]
	ds_read_b64_tr_b16 v[100:101], v235 offset:36864
	ds_read_b64_tr_b16 v[102:103], v235 offset:38400
	ds_read_b64_tr_b16 v[106:107], v235 offset:38464
	ds_read_b64_tr_b16 v[104:105], v235 offset:36928
	ds_read_b64_tr_b16 v[108:109], v235 offset:39936
	ds_read_b64_tr_b16 v[110:111], v235 offset:41472
	ds_read_b64_tr_b16 v[114:115], v235 offset:41536
	ds_read_b64_tr_b16 v[112:113], v235 offset:40000
	s_waitcnt lgkmcnt(14)
	v_mfma_f32_32x32x16_bf16 v[64:79], v[116:119], v[144:147], v[64:79]
	s_or_b32 s13, s12, 63
	v_cmp_ge_i32_e32 vcc, s12, v226
	v_cmp_le_u32_e64 s[16:17], s13, v246
	s_and_b64 s[16:17], vcc, s[16:17]
	s_nop 0
	s_cmp_eq_u64 s[16:17], exec
	s_cbranch_scc1 .LBB0_1017
	v_or_b32_e32 v0, s12, v237
	v_or_b32_e32 v1, 32, v0
	v_cmp_lt_i32_e64 s[18:19], v1, v226
	v_cmp_gt_u32_e64 s[20:21], v1, v246
	s_or_b64 s[18:19], s[18:19], s[20:21]
	v_or_b32_e32 v1, 1, v0
	v_cndmask_b32_e64 v64, v64, v244, s[18:19]
	v_cmp_ge_i32_e64 s[18:19], v1, v226
	v_or_b32_e32 v1, 33, v0
	v_cmp_lt_i32_e64 s[22:23], v1, v226
	v_cmp_gt_u32_e64 s[24:25], v1, v246
	s_or_b64 s[22:23], s[22:23], s[24:25]
	v_or_b32_e32 v1, 2, v0
	v_cndmask_b32_e64 v65, v65, v244, s[22:23]
	v_cmp_ge_i32_e64 s[22:23], v1, v226
	v_cmp_le_u32_e64 s[24:25], v1, v246
	v_or_b32_e32 v1, 34, v0
	v_cmp_lt_i32_e64 s[26:27], v1, v226
	v_cmp_gt_u32_e64 s[28:29], v1, v246
	v_or_b32_e32 v1, s12, v236
	s_or_b64 s[26:27], s[26:27], s[28:29]
	v_or_b32_e32 v3, 3, v1
	v_cndmask_b32_e64 v66, v66, v244, s[26:27]
	v_cmp_ge_i32_e64 s[26:27], v3, v226
	v_cmp_le_u32_e64 s[28:29], v3, v246
	v_or_b32_e32 v3, 35, v1
	v_cmp_lt_i32_e64 s[30:31], v3, v226
	v_cmp_gt_u32_e64 s[34:35], v3, v246
	s_or_b64 s[30:31], s[30:31], s[34:35]
	v_or_b32_e32 v3, 8, v0
	v_cndmask_b32_e64 v67, v67, v244, s[30:31]
	v_cmp_ge_i32_e64 s[30:31], v3, v226
	v_cmp_le_u32_e64 s[34:35], v3, v246
	v_or_b32_e32 v3, 40, v0
	v_cmp_lt_i32_e64 s[36:37], v3, v226
	v_cmp_gt_u32_e64 s[38:39], v3, v246
	s_or_b64 s[36:37], s[36:37], s[38:39]
	v_or_b32_e32 v3, 9, v0
	v_cndmask_b32_e64 v68, v68, v244, s[36:37]
	v_cmp_ge_i32_e64 s[36:37], v3, v226
	v_cmp_le_u32_e64 s[38:39], v3, v246
	v_or_b32_e32 v3, 41, v0
	v_cmp_lt_i32_e64 s[40:41], v3, v226
	v_cmp_gt_u32_e64 s[42:43], v3, v246
	s_or_b64 s[40:41], s[40:41], s[42:43]
	v_or_b32_e32 v3, 10, v0
	v_cndmask_b32_e64 v69, v69, v244, s[40:41]
	v_cmp_ge_i32_e64 s[40:41], v3, v226
	v_cmp_le_u32_e64 s[42:43], v3, v246
	v_or_b32_e32 v3, 42, v0
	v_cmp_lt_i32_e64 s[44:45], v3, v226
	v_cmp_gt_u32_e64 s[46:47], v3, v246
	s_or_b64 s[44:45], s[44:45], s[46:47]
	v_or_b32_e32 v3, 11, v1
	v_cndmask_b32_e64 v70, v70, v244, s[44:45]
	v_cmp_ge_i32_e64 s[44:45], v3, v226
	v_cmp_le_u32_e64 s[46:47], v3, v246
	v_or_b32_e32 v3, 43, v1
	v_cmp_lt_i32_e64 s[48:49], v3, v226
	v_cmp_gt_u32_e64 s[50:51], v3, v246
	s_or_b64 s[48:49], s[48:49], s[50:51]
	v_or_b32_e32 v3, 16, v0
	v_cndmask_b32_e64 v71, v71, v244, s[48:49]
	v_cmp_ge_i32_e64 s[48:49], v3, v226
	v_cmp_le_u32_e64 s[50:51], v3, v246
	v_or_b32_e32 v3, 48, v0
	v_cmp_lt_i32_e64 s[52:53], v3, v226
	v_cmp_gt_u32_e64 s[54:55], v3, v246
	s_or_b64 s[52:53], s[52:53], s[54:55]
	v_or_b32_e32 v3, 17, v0
	v_cndmask_b32_e64 v72, v72, v244, s[52:53]
	v_cmp_ge_i32_e64 s[52:53], v3, v226
	v_cmp_le_u32_e64 s[54:55], v3, v246
	v_or_b32_e32 v3, 49, v0
	v_cmp_lt_i32_e64 s[56:57], v3, v226
	v_cmp_gt_u32_e64 s[58:59], v3, v246
	s_or_b64 s[56:57], s[56:57], s[58:59]
	v_or_b32_e32 v3, 18, v0
	v_cndmask_b32_e64 v73, v73, v244, s[56:57]
	v_cmp_ge_i32_e64 s[56:57], v3, v226
	v_cmp_le_u32_e64 s[58:59], v3, v246
	v_or_b32_e32 v3, 50, v0
	v_cmp_lt_i32_e64 s[60:61], v3, v226
	v_cmp_gt_u32_e64 s[62:63], v3, v246
	s_or_b64 s[60:61], s[60:61], s[62:63]
	v_or_b32_e32 v3, 19, v1
	v_cndmask_b32_e64 v74, v74, v244, s[60:61]
	v_cmp_ge_i32_e64 s[60:61], v3, v226
	v_cmp_le_u32_e64 s[62:63], v3, v246
	v_or_b32_e32 v3, 51, v1
	v_cmp_lt_i32_e64 s[64:65], v3, v226
	v_cmp_gt_u32_e64 s[66:67], v3, v246
	s_or_b64 s[64:65], s[64:65], s[66:67]
	v_or_b32_e32 v3, 24, v0
	v_cndmask_b32_e64 v75, v75, v244, s[64:65]
	v_cmp_ge_i32_e64 s[64:65], v3, v226
	v_cmp_le_u32_e64 s[66:67], v3, v246
	v_or_b32_e32 v3, 56, v0
	v_cmp_lt_i32_e64 s[68:69], v3, v226
	v_cmp_gt_u32_e64 s[70:71], v3, v246
	s_or_b64 s[68:69], s[68:69], s[70:71]
	v_or_b32_e32 v3, 25, v0
	v_cndmask_b32_e64 v76, v76, v244, s[68:69]
	v_cmp_ge_i32_e64 s[68:69], v3, v226
	v_cmp_le_u32_e64 s[70:71], v3, v246
	v_or_b32_e32 v3, 57, v0
	v_cmp_ge_i32_e32 vcc, v0, v226
	v_cmp_le_u32_e64 s[16:17], v0, v246
	v_cmp_lt_u32_e64 s[20:21], v0, v246
	v_cmp_lt_i32_e64 s[72:73], v3, v226
	v_cmp_gt_u32_e64 s[74:75], v3, v246
	v_or_b32_e32 v3, 26, v0
	v_or_b32_e32 v0, 58, v0
	v_cmp_lt_i32_e64 s[76:77], v0, v226
	v_cmp_gt_u32_e64 s[78:79], v0, v246
	s_or_b64 s[76:77], s[76:77], s[78:79]
	v_or_b32_e32 v0, 27, v1
	v_cndmask_b32_e64 v78, v78, v244, s[76:77]
	v_cmp_ge_i32_e64 s[76:77], v0, v226
	v_cmp_le_u32_e64 s[78:79], v0, v246
	v_or_b32_e32 v0, 59, v1
	s_or_b64 s[72:73], s[72:73], s[74:75]
	v_cmp_lt_i32_e64 s[82:83], v0, v226
	v_cmp_gt_u32_e64 s[84:85], v0, v246
	v_cndmask_b32_e64 v77, v77, v244, s[72:73]
	v_cmp_ge_i32_e64 s[72:73], v3, v226
	v_cmp_le_u32_e64 s[74:75], v3, v246
	s_or_b64 s[82:83], s[82:83], s[84:85]
	s_and_saveexec_b64 s[12:13], s[82:83]
	v_mov_b32_e32 v79, s5
	s_or_b64 exec, exec, s[12:13]
	s_and_b64 vcc, vcc, s[16:17]
	v_cndmask_b32_e32 v80, v244, v80, vcc
	s_and_b64 vcc, s[20:21], s[18:19]
	v_cndmask_b32_e32 v81, v244, v81, vcc
	s_and_b64 vcc, s[22:23], s[24:25]
	v_cndmask_b32_e32 v82, v244, v82, vcc
	s_and_b64 vcc, s[26:27], s[28:29]
	v_cndmask_b32_e32 v83, v244, v83, vcc
	s_and_b64 vcc, s[30:31], s[34:35]
	v_cndmask_b32_e32 v84, v244, v84, vcc
	s_and_b64 vcc, s[36:37], s[38:39]
	v_cndmask_b32_e32 v85, v244, v85, vcc
	s_and_b64 vcc, s[40:41], s[42:43]
	v_cndmask_b32_e32 v86, v244, v86, vcc
	s_and_b64 vcc, s[44:45], s[46:47]
	v_cndmask_b32_e32 v87, v244, v87, vcc
	s_and_b64 vcc, s[48:49], s[50:51]
	v_cndmask_b32_e32 v88, v244, v88, vcc
	s_and_b64 vcc, s[52:53], s[54:55]
	v_cndmask_b32_e32 v89, v244, v89, vcc
	s_and_b64 vcc, s[56:57], s[58:59]
	v_cndmask_b32_e32 v90, v244, v90, vcc
	s_and_b64 vcc, s[60:61], s[62:63]
	v_cndmask_b32_e32 v91, v244, v91, vcc
	s_and_b64 vcc, s[64:65], s[66:67]
	v_cndmask_b32_e32 v92, v244, v92, vcc
	s_and_b64 vcc, s[68:69], s[70:71]
	v_cndmask_b32_e32 v93, v244, v93, vcc
	s_and_b64 vcc, s[72:73], s[74:75]
	v_cndmask_b32_e32 v94, v244, v94, vcc
	s_and_b64 vcc, s[76:77], s[78:79]
	v_cndmask_b32_e32 v95, v244, v95, vcc
.LBB0_1017:
	s_nop 3
	s_xor_b64 s[12:13], s[94:95], -1
	v_max3_f32 v0, v80, v81, v64
	v_max3_f32 v1, v82, v83, v65
	v_max3_f32 v0, v0, v66, v67
	v_max3_f32 v1, v1, v86, v87
	v_max3_f32 v0, v0, v84, v85
	v_max3_f32 v1, v1, v70, v71
	v_max3_f32 v0, v0, v68, v69
	v_max3_f32 v1, v1, v90, v91
	v_max3_f32 v0, v0, v88, v89
	v_max3_f32 v1, v1, v74, v75
	v_max3_f32 v0, v0, v72, v73
	v_max3_f32 v1, v1, v94, v95
	v_max3_f32 v0, v0, v92, v93
	v_max3_f32 v1, v1, v78, v79
	v_max3_f32 v0, v0, v76, v77
	v_max_f32_e32 v0, v0, v1
	v_mov_b32_e32 v1, v0
	s_nop 1
	v_permlane32_swap_b32_e32 v0, v1
	v_max_f32_e32 v1, v0, v1
	v_cmp_lt_f32_e32 vcc, s14, v1
	s_or_b64 s[16:17], vcc, s[12:13]
	s_cbranch_scc0 .LBB0_1023
	s_and_saveexec_b64 s[16:17], s[12:13]
	s_xor_b64 s[12:13], exec, s[16:17]
	v_cmp_lg_f32_e64 s[94:95], s5, v1
	s_nop 1
	v_cndmask_b32_e64 v48, 0, v1, s[94:95]
	s_or_saveexec_b64 s[12:13], s[12:13]
	v_mov_b32_e32 v0, 1.0
	s_xor_b64 exec, exec, s[12:13]
	v_max_f32_e32 v0, v1, v1
	v_max_f32_e32 v48, 0, v0
	v_exp_f32_e64 v0, -v48
	s_or_b64 s[94:95], s[94:95], exec
	s_or_b64 exec, exec, s[12:13]
	v_add_f32_e32 v248, v248, v48
	v_xor_b32_e32 v63, 0x80000000, v248
	v_pk_add_f32 v[80:81], v[80:81], v[48:49] op_sel_hi:[1,0] neg_lo:[0,1] neg_hi:[0,1]
	v_pk_add_f32 v[64:65], v[64:65], v[48:49] op_sel_hi:[1,0] neg_lo:[0,1] neg_hi:[0,1]
	v_pk_add_f32 v[82:83], v[82:83], v[48:49] op_sel_hi:[1,0] neg_lo:[0,1] neg_hi:[0,1]
	v_pk_add_f32 v[66:67], v[66:67], v[48:49] op_sel_hi:[1,0] neg_lo:[0,1] neg_hi:[0,1]
	v_pk_add_f32 v[84:85], v[84:85], v[48:49] op_sel_hi:[1,0] neg_lo:[0,1] neg_hi:[0,1]
	v_pk_add_f32 v[68:69], v[68:69], v[48:49] op_sel_hi:[1,0] neg_lo:[0,1] neg_hi:[0,1]
	v_pk_add_f32 v[86:87], v[86:87], v[48:49] op_sel_hi:[1,0] neg_lo:[0,1] neg_hi:[0,1]
	v_pk_add_f32 v[70:71], v[70:71], v[48:49] op_sel_hi:[1,0] neg_lo:[0,1] neg_hi:[0,1]
	v_pk_add_f32 v[88:89], v[88:89], v[48:49] op_sel_hi:[1,0] neg_lo:[0,1] neg_hi:[0,1]
	v_pk_add_f32 v[72:73], v[72:73], v[48:49] op_sel_hi:[1,0] neg_lo:[0,1] neg_hi:[0,1]
	v_pk_add_f32 v[90:91], v[90:91], v[48:49] op_sel_hi:[1,0] neg_lo:[0,1] neg_hi:[0,1]
	v_pk_add_f32 v[74:75], v[74:75], v[48:49] op_sel_hi:[1,0] neg_lo:[0,1] neg_hi:[0,1]
	v_pk_add_f32 v[92:93], v[92:93], v[48:49] op_sel_hi:[1,0] neg_lo:[0,1] neg_hi:[0,1]
	v_pk_add_f32 v[76:77], v[76:77], v[48:49] op_sel_hi:[1,0] neg_lo:[0,1] neg_hi:[0,1]
	v_pk_add_f32 v[94:95], v[94:95], v[48:49] op_sel_hi:[1,0] neg_lo:[0,1] neg_hi:[0,1]
	v_pk_add_f32 v[78:79], v[78:79], v[48:49] op_sel_hi:[1,0] neg_lo:[0,1] neg_hi:[0,1]
	v_mul_f32_e32 v222, v222, v0
	v_pk_mul_f32 v[46:47], v[46:47], v[0:1] op_sel_hi:[1,0]
	v_pk_mul_f32 v[44:45], v[44:45], v[0:1] op_sel_hi:[1,0]
	v_pk_mul_f32 v[42:43], v[42:43], v[0:1] op_sel_hi:[1,0]
	v_pk_mul_f32 v[40:41], v[40:41], v[0:1] op_sel_hi:[1,0]
	v_pk_mul_f32 v[38:39], v[38:39], v[0:1] op_sel_hi:[1,0]
	v_pk_mul_f32 v[36:37], v[36:37], v[0:1] op_sel_hi:[1,0]
	v_pk_mul_f32 v[34:35], v[34:35], v[0:1] op_sel_hi:[1,0]
	v_pk_mul_f32 v[32:33], v[32:33], v[0:1] op_sel_hi:[1,0]
	v_pk_mul_f32 v[30:31], v[30:31], v[0:1] op_sel_hi:[1,0]
	v_pk_mul_f32 v[28:29], v[28:29], v[0:1] op_sel_hi:[1,0]
	v_pk_mul_f32 v[26:27], v[26:27], v[0:1] op_sel_hi:[1,0]
	v_pk_mul_f32 v[24:25], v[24:25], v[0:1] op_sel_hi:[1,0]
	v_pk_mul_f32 v[22:23], v[22:23], v[0:1] op_sel_hi:[1,0]
	v_pk_mul_f32 v[20:21], v[20:21], v[0:1] op_sel_hi:[1,0]
	v_pk_mul_f32 v[18:19], v[18:19], v[0:1] op_sel_hi:[1,0]
	v_pk_mul_f32 v[16:17], v[16:17], v[0:1] op_sel_hi:[1,0]
	v_mov_b32_e32 v62, v63
	v_mov_b32_e32 v61, v63
	v_mov_b32_e32 v60, v63
	v_mov_b32_e32 v59, v63
	v_mov_b32_e32 v58, v63
	v_mov_b32_e32 v57, v63
	v_mov_b32_e32 v56, v63
	v_mov_b32_e32 v55, v63
	v_mov_b32_e32 v54, v63
	v_mov_b32_e32 v53, v63
	v_mov_b32_e32 v52, v63
	v_mov_b32_e32 v51, v63
	v_mov_b32_e32 v50, v63
	v_mov_b32_e32 v49, v63
	v_mov_b32_e32 v48, v63
